# scan block start waits only for the first step's operands (lgkmcnt(6) instead of 0)
# speedup vs baseline: 1.0088x; 1.0088x over previous
.LBB0_685:
	ds_read_b128 v[164:167], v5 offset:0
	ds_read_b128 v[168:171], v5 offset:256
	ds_read_b128 v[172:175], v5 offset:512
	ds_read_b128 v[176:179], v5 offset:768
	ds_read_b128 v[180:183], v5 offset:1024
	ds_read_b32 v184, v9 offset:0
	ds_read_b128 v[186:189], v5 offset:1536
	ds_read_b128 v[190:193], v5 offset:1792
	ds_read_b128 v[194:197], v5 offset:2048
	ds_read_b128 v[198:201], v5 offset:2304
	ds_read_b128 v[202:205], v5 offset:2560
	ds_read_b32 v206, v9 offset:1536
	s_waitcnt lgkmcnt(6)
	v_pk_mul_f32 v[144:145], v[138:139], v[164:165]
	v_pk_fma_f32 v[144:145], v[140:141], v[166:167], v[144:145]
	v_add_f32 v146, v144, v145
	ds_read_b128 v[208:211], v5 offset:3072
	ds_read_b128 v[212:215], v5 offset:3328
	ds_read_b128 v[216:219], v5 offset:3584
	ds_read_b128 v[220:223], v5 offset:3840
	ds_read_b128 v[224:227], v5 offset:4096
	ds_read_b32 v228, v9 offset:3072
	v_add_f32_dpp v146, v146, v146 quad_perm:[1,0,3,2] row_mask:0xf bank_mask:0xf bound_ctrl:1
	s_nop 0
	s_nop 0
	v_add_f32_dpp v146, v146, v146 quad_perm:[2,3,0,1] row_mask:0xf bank_mask:0xf bound_ctrl:1
	s_nop 0
	v_pk_mul_f32 v[176:177], v[176:177], v[184:185] op_sel_hi:[1,0]
	v_add_f32_dpp v146, v146, v146 row_half_mirror row_mask:0xf bank_mask:0xf bound_ctrl:1
	v_pk_mul_f32 v[178:179], v[178:179], v[184:185] op_sel_hi:[1,0]
	s_waitcnt lgkmcnt(6)
	v_add_f32_dpp v146, v146, v146 row_mirror row_mask:0xf bank_mask:0xf bound_ctrl:1
	v_pk_fma_f32 v[176:177], v[146:147], v[168:169], v[176:177] op_sel_hi:[0,1,1] neg_lo:[1,0,0] neg_hi:[1,0,0]
	v_pk_fma_f32 v[178:179], v[146:147], v[170:171], v[178:179] op_sel_hi:[0,1,1] neg_lo:[1,0,0] neg_hi:[1,0,0]
	v_pk_fma_f32 v[138:139], v[138:139], v[172:173], v[176:177]
	v_pk_fma_f32 v[140:141], v[140:141], v[174:175], v[178:179]
	v_pk_mul_f32 v[144:145], v[138:139], v[186:187]
	v_pk_fma_f32 v[144:145], v[140:141], v[188:189], v[144:145]
	v_add_f32 v146, v144, v145
	ds_read_b128 v[230:233], v5 offset:4608
	ds_read_b128 v[234:237], v5 offset:4864
	ds_read_b128 v[238:241], v5 offset:5120
	ds_read_b128 v[242:245], v5 offset:5376
	ds_read_b128 v[246:249], v5 offset:5632
	ds_read_b32 v250, v9 offset:4608
	v_add_f32_dpp v146, v146, v146 quad_perm:[1,0,3,2] row_mask:0xf bank_mask:0xf bound_ctrl:1
	v_pk_mul_f32 v[180:181], v[138:139], v[180:181]
	v_pk_fma_f32 v[180:181], v[140:141], v[182:183], v[180:181]
	v_add_f32_dpp v146, v146, v146 quad_perm:[2,3,0,1] row_mask:0xf bank_mask:0xf bound_ctrl:1
	v_add_f32 v148, v180, v181
	v_pk_mul_f32 v[198:199], v[198:199], v[206:207] op_sel_hi:[1,0]
	v_add_f32_dpp v146, v146, v146 row_half_mirror row_mask:0xf bank_mask:0xf bound_ctrl:1
	v_pk_mul_f32 v[200:201], v[200:201], v[206:207] op_sel_hi:[1,0]
	s_waitcnt lgkmcnt(6)
	v_add_f32_dpp v146, v146, v146 row_mirror row_mask:0xf bank_mask:0xf bound_ctrl:1
	v_pk_fma_f32 v[198:199], v[146:147], v[190:191], v[198:199] op_sel_hi:[0,1,1] neg_lo:[1,0,0] neg_hi:[1,0,0]
	v_pk_fma_f32 v[200:201], v[146:147], v[192:193], v[200:201] op_sel_hi:[0,1,1] neg_lo:[1,0,0] neg_hi:[1,0,0]
	v_pk_fma_f32 v[138:139], v[138:139], v[194:195], v[198:199]
	v_pk_fma_f32 v[140:141], v[140:141], v[196:197], v[200:201]
	v_pk_mul_f32 v[144:145], v[138:139], v[208:209]
	v_pk_fma_f32 v[144:145], v[140:141], v[210:211], v[144:145]
	v_add_f32 v146, v144, v145
	ds_read_b128 v[164:167], v5 offset:6144
	ds_read_b128 v[168:171], v5 offset:6400
	ds_read_b128 v[172:175], v5 offset:6656
	ds_read_b128 v[176:179], v5 offset:6912
	ds_read_b128 v[180:183], v5 offset:7168
	ds_read_b32 v184, v9 offset:6144
	v_add_f32_dpp v146, v146, v146 quad_perm:[1,0,3,2] row_mask:0xf bank_mask:0xf bound_ctrl:1
	v_pk_mul_f32 v[202:203], v[138:139], v[202:203]
	v_pk_fma_f32 v[202:203], v[140:141], v[204:205], v[202:203]
	v_add_f32_dpp v146, v146, v146 quad_perm:[2,3,0,1] row_mask:0xf bank_mask:0xf bound_ctrl:1
	v_add_f32 v149, v202, v203
	v_pk_mul_f32 v[220:221], v[220:221], v[228:229] op_sel_hi:[1,0]
	v_add_f32_dpp v146, v146, v146 row_half_mirror row_mask:0xf bank_mask:0xf bound_ctrl:1
	v_pk_mul_f32 v[222:223], v[222:223], v[228:229] op_sel_hi:[1,0]
	s_waitcnt lgkmcnt(6)
	v_add_f32_dpp v146, v146, v146 row_mirror row_mask:0xf bank_mask:0xf bound_ctrl:1
	v_pk_fma_f32 v[220:221], v[146:147], v[212:213], v[220:221] op_sel_hi:[0,1,1] neg_lo:[1,0,0] neg_hi:[1,0,0]
	v_pk_fma_f32 v[222:223], v[146:147], v[214:215], v[222:223] op_sel_hi:[0,1,1] neg_lo:[1,0,0] neg_hi:[1,0,0]
	v_pk_fma_f32 v[138:139], v[138:139], v[216:217], v[220:221]
	v_pk_fma_f32 v[140:141], v[140:141], v[218:219], v[222:223]
	v_pk_mul_f32 v[144:145], v[138:139], v[230:231]
	v_pk_fma_f32 v[144:145], v[140:141], v[232:233], v[144:145]
	v_add_f32 v146, v144, v145
	ds_read_b128 v[186:189], v5 offset:7680
	ds_read_b128 v[190:193], v5 offset:7936
	ds_read_b128 v[194:197], v5 offset:8192
	ds_read_b128 v[198:201], v5 offset:8448
	ds_read_b128 v[202:205], v5 offset:8704
	ds_read_b32 v206, v9 offset:7680
	v_add_f32_dpp v146, v146, v146 quad_perm:[1,0,3,2] row_mask:0xf bank_mask:0xf bound_ctrl:1
	v_pk_mul_f32 v[224:225], v[138:139], v[224:225]
	v_pk_fma_f32 v[224:225], v[140:141], v[226:227], v[224:225]
	v_add_f32_dpp v146, v146, v146 quad_perm:[2,3,0,1] row_mask:0xf bank_mask:0xf bound_ctrl:1
	v_add_f32 v150, v224, v225
	v_pk_mul_f32 v[242:243], v[242:243], v[250:251] op_sel_hi:[1,0]
	v_add_f32_dpp v146, v146, v146 row_half_mirror row_mask:0xf bank_mask:0xf bound_ctrl:1
	v_pk_mul_f32 v[244:245], v[244:245], v[250:251] op_sel_hi:[1,0]
	s_waitcnt lgkmcnt(6)
	v_add_f32_dpp v146, v146, v146 row_mirror row_mask:0xf bank_mask:0xf bound_ctrl:1
	v_pk_fma_f32 v[242:243], v[146:147], v[234:235], v[242:243] op_sel_hi:[0,1,1] neg_lo:[1,0,0] neg_hi:[1,0,0]
	v_pk_fma_f32 v[244:245], v[146:147], v[236:237], v[244:245] op_sel_hi:[0,1,1] neg_lo:[1,0,0] neg_hi:[1,0,0]
	v_pk_fma_f32 v[138:139], v[138:139], v[238:239], v[242:243]
	v_pk_fma_f32 v[140:141], v[140:141], v[240:241], v[244:245]
	v_pk_mul_f32 v[144:145], v[138:139], v[164:165]
	v_pk_fma_f32 v[144:145], v[140:141], v[166:167], v[144:145]
	v_add_f32 v146, v144, v145
	ds_read_b128 v[208:211], v5 offset:9216
	ds_read_b128 v[212:215], v5 offset:9472
	ds_read_b128 v[216:219], v5 offset:9728
	ds_read_b128 v[220:223], v5 offset:9984
	ds_read_b128 v[224:227], v5 offset:10240
	ds_read_b32 v228, v9 offset:9216
	v_add_f32_dpp v146, v146, v146 quad_perm:[1,0,3,2] row_mask:0xf bank_mask:0xf bound_ctrl:1
	v_pk_mul_f32 v[246:247], v[138:139], v[246:247]
	v_pk_fma_f32 v[246:247], v[140:141], v[248:249], v[246:247]
	v_add_f32_dpp v146, v146, v146 quad_perm:[2,3,0,1] row_mask:0xf bank_mask:0xf bound_ctrl:1
	v_add_f32 v151, v246, v247
	v_pk_mul_f32 v[176:177], v[176:177], v[184:185] op_sel_hi:[1,0]
	v_add_f32_dpp v146, v146, v146 row_half_mirror row_mask:0xf bank_mask:0xf bound_ctrl:1
	v_pk_mul_f32 v[178:179], v[178:179], v[184:185] op_sel_hi:[1,0]
	s_waitcnt lgkmcnt(6)
	v_add_f32_dpp v146, v146, v146 row_mirror row_mask:0xf bank_mask:0xf bound_ctrl:1
	v_pk_fma_f32 v[176:177], v[146:147], v[168:169], v[176:177] op_sel_hi:[0,1,1] neg_lo:[1,0,0] neg_hi:[1,0,0]
	v_pk_fma_f32 v[178:179], v[146:147], v[170:171], v[178:179] op_sel_hi:[0,1,1] neg_lo:[1,0,0] neg_hi:[1,0,0]
	v_pk_fma_f32 v[138:139], v[138:139], v[172:173], v[176:177]
	v_pk_fma_f32 v[140:141], v[140:141], v[174:175], v[178:179]
	v_pk_mul_f32 v[144:145], v[138:139], v[186:187]
	v_pk_fma_f32 v[144:145], v[140:141], v[188:189], v[144:145]
	v_add_f32 v146, v144, v145
	ds_read_b128 v[230:233], v5 offset:10752
	ds_read_b128 v[234:237], v5 offset:11008
	ds_read_b128 v[238:241], v5 offset:11264
	ds_read_b128 v[242:245], v5 offset:11520
	ds_read_b128 v[246:249], v5 offset:11776
	ds_read_b32 v250, v9 offset:10752
	v_add_f32_dpp v146, v146, v146 quad_perm:[1,0,3,2] row_mask:0xf bank_mask:0xf bound_ctrl:1
	v_pk_mul_f32 v[180:181], v[138:139], v[180:181]
	v_pk_fma_f32 v[180:181], v[140:141], v[182:183], v[180:181]
	v_add_f32_dpp v146, v146, v146 quad_perm:[2,3,0,1] row_mask:0xf bank_mask:0xf bound_ctrl:1
	v_add_f32 v152, v180, v181
	v_pk_mul_f32 v[198:199], v[198:199], v[206:207] op_sel_hi:[1,0]
	v_add_f32_dpp v146, v146, v146 row_half_mirror row_mask:0xf bank_mask:0xf bound_ctrl:1
	v_pk_mul_f32 v[200:201], v[200:201], v[206:207] op_sel_hi:[1,0]
	s_waitcnt lgkmcnt(6)
	v_add_f32_dpp v146, v146, v146 row_mirror row_mask:0xf bank_mask:0xf bound_ctrl:1
	v_pk_fma_f32 v[198:199], v[146:147], v[190:191], v[198:199] op_sel_hi:[0,1,1] neg_lo:[1,0,0] neg_hi:[1,0,0]
	v_pk_fma_f32 v[200:201], v[146:147], v[192:193], v[200:201] op_sel_hi:[0,1,1] neg_lo:[1,0,0] neg_hi:[1,0,0]
	v_pk_fma_f32 v[138:139], v[138:139], v[194:195], v[198:199]
	v_pk_fma_f32 v[140:141], v[140:141], v[196:197], v[200:201]
	v_pk_mul_f32 v[144:145], v[138:139], v[208:209]
	v_pk_fma_f32 v[144:145], v[140:141], v[210:211], v[144:145]
	v_add_f32 v146, v144, v145
	ds_read_b128 v[164:167], v5 offset:12288
	ds_read_b128 v[168:171], v5 offset:12544
	ds_read_b128 v[172:175], v5 offset:12800
	ds_read_b128 v[176:179], v5 offset:13056
	ds_read_b128 v[180:183], v5 offset:13312
	ds_read_b32 v184, v9 offset:12288
	v_add_f32_dpp v146, v146, v146 quad_perm:[1,0,3,2] row_mask:0xf bank_mask:0xf bound_ctrl:1
	v_pk_mul_f32 v[202:203], v[138:139], v[202:203]
	v_pk_fma_f32 v[202:203], v[140:141], v[204:205], v[202:203]
	v_add_f32_dpp v146, v146, v146 quad_perm:[2,3,0,1] row_mask:0xf bank_mask:0xf bound_ctrl:1
	v_add_f32 v153, v202, v203
	v_pk_mul_f32 v[220:221], v[220:221], v[228:229] op_sel_hi:[1,0]
	v_add_f32_dpp v146, v146, v146 row_half_mirror row_mask:0xf bank_mask:0xf bound_ctrl:1
	v_pk_mul_f32 v[222:223], v[222:223], v[228:229] op_sel_hi:[1,0]
	s_waitcnt lgkmcnt(6)
	v_add_f32_dpp v146, v146, v146 row_mirror row_mask:0xf bank_mask:0xf bound_ctrl:1
	v_pk_fma_f32 v[220:221], v[146:147], v[212:213], v[220:221] op_sel_hi:[0,1,1] neg_lo:[1,0,0] neg_hi:[1,0,0]
	v_pk_fma_f32 v[222:223], v[146:147], v[214:215], v[222:223] op_sel_hi:[0,1,1] neg_lo:[1,0,0] neg_hi:[1,0,0]
	v_pk_fma_f32 v[138:139], v[138:139], v[216:217], v[220:221]
	v_pk_fma_f32 v[140:141], v[140:141], v[218:219], v[222:223]
	v_pk_mul_f32 v[144:145], v[138:139], v[230:231]
	v_pk_fma_f32 v[144:145], v[140:141], v[232:233], v[144:145]
	v_add_f32 v146, v144, v145
	ds_read_b128 v[186:189], v5 offset:13824
	ds_read_b128 v[190:193], v5 offset:14080
	ds_read_b128 v[194:197], v5 offset:14336
	ds_read_b128 v[198:201], v5 offset:14592
	ds_read_b128 v[202:205], v5 offset:14848
	ds_read_b32 v206, v9 offset:13824
	v_add_f32_dpp v146, v146, v146 quad_perm:[1,0,3,2] row_mask:0xf bank_mask:0xf bound_ctrl:1
	v_pk_mul_f32 v[224:225], v[138:139], v[224:225]
	v_pk_fma_f32 v[224:225], v[140:141], v[226:227], v[224:225]
	v_add_f32_dpp v146, v146, v146 quad_perm:[2,3,0,1] row_mask:0xf bank_mask:0xf bound_ctrl:1
	v_add_f32 v154, v224, v225
	v_pk_mul_f32 v[242:243], v[242:243], v[250:251] op_sel_hi:[1,0]
	v_add_f32_dpp v146, v146, v146 row_half_mirror row_mask:0xf bank_mask:0xf bound_ctrl:1
	v_pk_mul_f32 v[244:245], v[244:245], v[250:251] op_sel_hi:[1,0]
	s_waitcnt lgkmcnt(6)
	v_add_f32_dpp v146, v146, v146 row_mirror row_mask:0xf bank_mask:0xf bound_ctrl:1
	v_pk_fma_f32 v[242:243], v[146:147], v[234:235], v[242:243] op_sel_hi:[0,1,1] neg_lo:[1,0,0] neg_hi:[1,0,0]
	v_pk_fma_f32 v[244:245], v[146:147], v[236:237], v[244:245] op_sel_hi:[0,1,1] neg_lo:[1,0,0] neg_hi:[1,0,0]
	v_pk_fma_f32 v[138:139], v[138:139], v[238:239], v[242:243]
	v_pk_fma_f32 v[140:141], v[140:141], v[240:241], v[244:245]
	v_pk_mul_f32 v[144:145], v[138:139], v[164:165]
	v_pk_fma_f32 v[144:145], v[140:141], v[166:167], v[144:145]
	v_add_f32 v146, v144, v145
	ds_read_b128 v[208:211], v5 offset:15360
	ds_read_b128 v[212:215], v5 offset:15616
	ds_read_b128 v[216:219], v5 offset:15872
	ds_read_b128 v[220:223], v5 offset:16128
	ds_read_b128 v[224:227], v5 offset:16384
	ds_read_b32 v228, v9 offset:15360
	v_add_f32_dpp v146, v146, v146 quad_perm:[1,0,3,2] row_mask:0xf bank_mask:0xf bound_ctrl:1
	v_pk_mul_f32 v[246:247], v[138:139], v[246:247]
	v_pk_fma_f32 v[246:247], v[140:141], v[248:249], v[246:247]
	v_add_f32_dpp v146, v146, v146 quad_perm:[2,3,0,1] row_mask:0xf bank_mask:0xf bound_ctrl:1
	v_add_f32 v155, v246, v247
	v_pk_mul_f32 v[176:177], v[176:177], v[184:185] op_sel_hi:[1,0]
	v_add_f32_dpp v146, v146, v146 row_half_mirror row_mask:0xf bank_mask:0xf bound_ctrl:1
	v_pk_mul_f32 v[178:179], v[178:179], v[184:185] op_sel_hi:[1,0]
	s_waitcnt lgkmcnt(6)
	v_add_f32_dpp v146, v146, v146 row_mirror row_mask:0xf bank_mask:0xf bound_ctrl:1
	v_pk_fma_f32 v[176:177], v[146:147], v[168:169], v[176:177] op_sel_hi:[0,1,1] neg_lo:[1,0,0] neg_hi:[1,0,0]
	v_pk_fma_f32 v[178:179], v[146:147], v[170:171], v[178:179] op_sel_hi:[0,1,1] neg_lo:[1,0,0] neg_hi:[1,0,0]
	v_pk_fma_f32 v[138:139], v[138:139], v[172:173], v[176:177]
	v_pk_fma_f32 v[140:141], v[140:141], v[174:175], v[178:179]
	v_pk_mul_f32 v[144:145], v[138:139], v[186:187]
	v_pk_fma_f32 v[144:145], v[140:141], v[188:189], v[144:145]
	v_add_f32 v146, v144, v145
	ds_read_b128 v[230:233], v5 offset:16896
	ds_read_b128 v[234:237], v5 offset:17152
	ds_read_b128 v[238:241], v5 offset:17408
	ds_read_b128 v[242:245], v5 offset:17664
	ds_read_b128 v[246:249], v5 offset:17920
	ds_read_b32 v250, v9 offset:16896
	v_add_f32_dpp v146, v146, v146 quad_perm:[1,0,3,2] row_mask:0xf bank_mask:0xf bound_ctrl:1
	v_pk_mul_f32 v[180:181], v[138:139], v[180:181]
	v_pk_fma_f32 v[180:181], v[140:141], v[182:183], v[180:181]
	v_add_f32_dpp v146, v146, v146 quad_perm:[2,3,0,1] row_mask:0xf bank_mask:0xf bound_ctrl:1
	v_add_f32 v156, v180, v181
	v_pk_mul_f32 v[198:199], v[198:199], v[206:207] op_sel_hi:[1,0]
	v_add_f32_dpp v146, v146, v146 row_half_mirror row_mask:0xf bank_mask:0xf bound_ctrl:1
	v_pk_mul_f32 v[200:201], v[200:201], v[206:207] op_sel_hi:[1,0]
	s_waitcnt lgkmcnt(6)
	v_add_f32_dpp v146, v146, v146 row_mirror row_mask:0xf bank_mask:0xf bound_ctrl:1
	v_pk_fma_f32 v[198:199], v[146:147], v[190:191], v[198:199] op_sel_hi:[0,1,1] neg_lo:[1,0,0] neg_hi:[1,0,0]
	v_pk_fma_f32 v[200:201], v[146:147], v[192:193], v[200:201] op_sel_hi:[0,1,1] neg_lo:[1,0,0] neg_hi:[1,0,0]
	v_pk_fma_f32 v[138:139], v[138:139], v[194:195], v[198:199]
	v_pk_fma_f32 v[140:141], v[140:141], v[196:197], v[200:201]
	v_pk_mul_f32 v[144:145], v[138:139], v[208:209]
	v_pk_fma_f32 v[144:145], v[140:141], v[210:211], v[144:145]
	v_add_f32 v146, v144, v145
	ds_read_b128 v[164:167], v5 offset:18432
	ds_read_b128 v[168:171], v5 offset:18688
	ds_read_b128 v[172:175], v5 offset:18944
	ds_read_b128 v[176:179], v5 offset:19200
	ds_read_b128 v[180:183], v5 offset:19456
	ds_read_b32 v184, v9 offset:18432
	v_add_f32_dpp v146, v146, v146 quad_perm:[1,0,3,2] row_mask:0xf bank_mask:0xf bound_ctrl:1
	v_pk_mul_f32 v[202:203], v[138:139], v[202:203]
	v_pk_fma_f32 v[202:203], v[140:141], v[204:205], v[202:203]
	v_add_f32_dpp v146, v146, v146 quad_perm:[2,3,0,1] row_mask:0xf bank_mask:0xf bound_ctrl:1
	v_add_f32 v157, v202, v203
	v_pk_mul_f32 v[220:221], v[220:221], v[228:229] op_sel_hi:[1,0]
	v_add_f32_dpp v146, v146, v146 row_half_mirror row_mask:0xf bank_mask:0xf bound_ctrl:1
	v_pk_mul_f32 v[222:223], v[222:223], v[228:229] op_sel_hi:[1,0]
	s_waitcnt lgkmcnt(6)
	v_add_f32_dpp v146, v146, v146 row_mirror row_mask:0xf bank_mask:0xf bound_ctrl:1
	v_pk_fma_f32 v[220:221], v[146:147], v[212:213], v[220:221] op_sel_hi:[0,1,1] neg_lo:[1,0,0] neg_hi:[1,0,0]
	v_pk_fma_f32 v[222:223], v[146:147], v[214:215], v[222:223] op_sel_hi:[0,1,1] neg_lo:[1,0,0] neg_hi:[1,0,0]
	v_pk_fma_f32 v[138:139], v[138:139], v[216:217], v[220:221]
	v_pk_fma_f32 v[140:141], v[140:141], v[218:219], v[222:223]
	v_pk_mul_f32 v[144:145], v[138:139], v[230:231]
	v_pk_fma_f32 v[144:145], v[140:141], v[232:233], v[144:145]
	v_add_f32 v146, v144, v145
	ds_read_b128 v[186:189], v5 offset:19968
	ds_read_b128 v[190:193], v5 offset:20224
	ds_read_b128 v[194:197], v5 offset:20480
	ds_read_b128 v[198:201], v5 offset:20736
	ds_read_b128 v[202:205], v5 offset:20992
	ds_read_b32 v206, v9 offset:19968
	v_add_f32_dpp v146, v146, v146 quad_perm:[1,0,3,2] row_mask:0xf bank_mask:0xf bound_ctrl:1
	v_pk_mul_f32 v[224:225], v[138:139], v[224:225]
	v_pk_fma_f32 v[224:225], v[140:141], v[226:227], v[224:225]
	v_add_f32_dpp v146, v146, v146 quad_perm:[2,3,0,1] row_mask:0xf bank_mask:0xf bound_ctrl:1
	v_add_f32 v158, v224, v225
	v_pk_mul_f32 v[242:243], v[242:243], v[250:251] op_sel_hi:[1,0]
	v_add_f32_dpp v146, v146, v146 row_half_mirror row_mask:0xf bank_mask:0xf bound_ctrl:1
	v_pk_mul_f32 v[244:245], v[244:245], v[250:251] op_sel_hi:[1,0]
	s_waitcnt lgkmcnt(6)
	v_add_f32_dpp v146, v146, v146 row_mirror row_mask:0xf bank_mask:0xf bound_ctrl:1
	v_pk_fma_f32 v[242:243], v[146:147], v[234:235], v[242:243] op_sel_hi:[0,1,1] neg_lo:[1,0,0] neg_hi:[1,0,0]
	v_pk_fma_f32 v[244:245], v[146:147], v[236:237], v[244:245] op_sel_hi:[0,1,1] neg_lo:[1,0,0] neg_hi:[1,0,0]
	v_pk_fma_f32 v[138:139], v[138:139], v[238:239], v[242:243]
	v_pk_fma_f32 v[140:141], v[140:141], v[240:241], v[244:245]
	v_pk_mul_f32 v[144:145], v[138:139], v[164:165]
	v_pk_fma_f32 v[144:145], v[140:141], v[166:167], v[144:145]
	v_add_f32 v146, v144, v145
	ds_read_b128 v[208:211], v5 offset:21504
	ds_read_b128 v[212:215], v5 offset:21760
	ds_read_b128 v[216:219], v5 offset:22016
	ds_read_b128 v[220:223], v5 offset:22272
	ds_read_b128 v[224:227], v5 offset:22528
	ds_read_b32 v228, v9 offset:21504
	v_add_f32_dpp v146, v146, v146 quad_perm:[1,0,3,2] row_mask:0xf bank_mask:0xf bound_ctrl:1
	v_pk_mul_f32 v[246:247], v[138:139], v[246:247]
	v_pk_fma_f32 v[246:247], v[140:141], v[248:249], v[246:247]
	v_add_f32_dpp v146, v146, v146 quad_perm:[2,3,0,1] row_mask:0xf bank_mask:0xf bound_ctrl:1
	v_add_f32 v159, v246, v247
	v_pk_mul_f32 v[176:177], v[176:177], v[184:185] op_sel_hi:[1,0]
	v_add_f32_dpp v146, v146, v146 row_half_mirror row_mask:0xf bank_mask:0xf bound_ctrl:1
	v_pk_mul_f32 v[178:179], v[178:179], v[184:185] op_sel_hi:[1,0]
	s_waitcnt lgkmcnt(6)
	v_add_f32_dpp v146, v146, v146 row_mirror row_mask:0xf bank_mask:0xf bound_ctrl:1
	v_pk_fma_f32 v[176:177], v[146:147], v[168:169], v[176:177] op_sel_hi:[0,1,1] neg_lo:[1,0,0] neg_hi:[1,0,0]
	v_pk_fma_f32 v[178:179], v[146:147], v[170:171], v[178:179] op_sel_hi:[0,1,1] neg_lo:[1,0,0] neg_hi:[1,0,0]
	v_pk_fma_f32 v[138:139], v[138:139], v[172:173], v[176:177]
	v_pk_fma_f32 v[140:141], v[140:141], v[174:175], v[178:179]
	v_pk_mul_f32 v[144:145], v[138:139], v[186:187]
	v_pk_fma_f32 v[144:145], v[140:141], v[188:189], v[144:145]
	v_add_f32 v146, v144, v145
	ds_read_b128 v[230:233], v5 offset:23040
	ds_read_b128 v[234:237], v5 offset:23296
	ds_read_b128 v[238:241], v5 offset:23552
	ds_read_b128 v[242:245], v5 offset:23808
	ds_read_b128 v[246:249], v5 offset:24064
	ds_read_b32 v250, v9 offset:23040
	v_add_f32_dpp v146, v146, v146 quad_perm:[1,0,3,2] row_mask:0xf bank_mask:0xf bound_ctrl:1
	v_pk_mul_f32 v[180:181], v[138:139], v[180:181]
	v_pk_fma_f32 v[180:181], v[140:141], v[182:183], v[180:181]
	v_add_f32_dpp v146, v146, v146 quad_perm:[2,3,0,1] row_mask:0xf bank_mask:0xf bound_ctrl:1
	v_add_f32 v160, v180, v181
	v_pk_mul_f32 v[198:199], v[198:199], v[206:207] op_sel_hi:[1,0]
	v_add_f32_dpp v146, v146, v146 row_half_mirror row_mask:0xf bank_mask:0xf bound_ctrl:1
	v_pk_mul_f32 v[200:201], v[200:201], v[206:207] op_sel_hi:[1,0]
	s_waitcnt lgkmcnt(6)
	v_add_f32_dpp v146, v146, v146 row_mirror row_mask:0xf bank_mask:0xf bound_ctrl:1
	v_pk_fma_f32 v[198:199], v[146:147], v[190:191], v[198:199] op_sel_hi:[0,1,1] neg_lo:[1,0,0] neg_hi:[1,0,0]
	v_pk_fma_f32 v[200:201], v[146:147], v[192:193], v[200:201] op_sel_hi:[0,1,1] neg_lo:[1,0,0] neg_hi:[1,0,0]
	v_pk_fma_f32 v[138:139], v[138:139], v[194:195], v[198:199]
	v_pk_fma_f32 v[140:141], v[140:141], v[196:197], v[200:201]
	v_pk_mul_f32 v[144:145], v[138:139], v[208:209]
	v_pk_fma_f32 v[144:145], v[140:141], v[210:211], v[144:145]
	v_add_f32 v146, v144, v145
	ds_read_b128 v[164:167], v5 offset:24576
	ds_read_b128 v[168:171], v5 offset:24832
	ds_read_b128 v[172:175], v5 offset:25088
	ds_read_b128 v[176:179], v5 offset:25344
	ds_read_b128 v[180:183], v5 offset:25600
	ds_read_b32 v184, v9 offset:24576
	v_add_f32_dpp v146, v146, v146 quad_perm:[1,0,3,2] row_mask:0xf bank_mask:0xf bound_ctrl:1
	v_pk_mul_f32 v[202:203], v[138:139], v[202:203]
	v_pk_fma_f32 v[202:203], v[140:141], v[204:205], v[202:203]
	v_add_f32_dpp v146, v146, v146 quad_perm:[2,3,0,1] row_mask:0xf bank_mask:0xf bound_ctrl:1
	v_add_f32 v161, v202, v203
	v_pk_mul_f32 v[220:221], v[220:221], v[228:229] op_sel_hi:[1,0]
	v_add_f32_dpp v146, v146, v146 row_half_mirror row_mask:0xf bank_mask:0xf bound_ctrl:1
	v_pk_mul_f32 v[222:223], v[222:223], v[228:229] op_sel_hi:[1,0]
	s_waitcnt lgkmcnt(6)
	v_add_f32_dpp v146, v146, v146 row_mirror row_mask:0xf bank_mask:0xf bound_ctrl:1
	v_pk_fma_f32 v[220:221], v[146:147], v[212:213], v[220:221] op_sel_hi:[0,1,1] neg_lo:[1,0,0] neg_hi:[1,0,0]
	v_pk_fma_f32 v[222:223], v[146:147], v[214:215], v[222:223] op_sel_hi:[0,1,1] neg_lo:[1,0,0] neg_hi:[1,0,0]
	v_pk_fma_f32 v[138:139], v[138:139], v[216:217], v[220:221]
	v_pk_fma_f32 v[140:141], v[140:141], v[218:219], v[222:223]
	v_pk_mul_f32 v[144:145], v[138:139], v[230:231]
	v_pk_fma_f32 v[144:145], v[140:141], v[232:233], v[144:145]
	v_add_f32 v146, v144, v145
	ds_read_b128 v[186:189], v5 offset:26112
	ds_read_b128 v[190:193], v5 offset:26368
	ds_read_b128 v[194:197], v5 offset:26624
	ds_read_b128 v[198:201], v5 offset:26880
	ds_read_b128 v[202:205], v5 offset:27136
	ds_read_b32 v206, v9 offset:26112
	v_add_f32_dpp v146, v146, v146 quad_perm:[1,0,3,2] row_mask:0xf bank_mask:0xf bound_ctrl:1
	v_pk_mul_f32 v[224:225], v[138:139], v[224:225]
	v_pk_fma_f32 v[224:225], v[140:141], v[226:227], v[224:225]
	v_add_f32_dpp v146, v146, v146 quad_perm:[2,3,0,1] row_mask:0xf bank_mask:0xf bound_ctrl:1
	v_add_f32 v162, v224, v225
	v_pk_mul_f32 v[242:243], v[242:243], v[250:251] op_sel_hi:[1,0]
	v_add_f32_dpp v146, v146, v146 row_half_mirror row_mask:0xf bank_mask:0xf bound_ctrl:1
	v_pk_mul_f32 v[244:245], v[244:245], v[250:251] op_sel_hi:[1,0]
	s_waitcnt lgkmcnt(6)
	v_add_f32_dpp v146, v146, v146 row_mirror row_mask:0xf bank_mask:0xf bound_ctrl:1
	v_pk_fma_f32 v[242:243], v[146:147], v[234:235], v[242:243] op_sel_hi:[0,1,1] neg_lo:[1,0,0] neg_hi:[1,0,0]
	v_pk_fma_f32 v[244:245], v[146:147], v[236:237], v[244:245] op_sel_hi:[0,1,1] neg_lo:[1,0,0] neg_hi:[1,0,0]
	v_pk_fma_f32 v[138:139], v[138:139], v[238:239], v[242:243]
	v_pk_fma_f32 v[140:141], v[140:141], v[240:241], v[244:245]
	v_pk_mul_f32 v[144:145], v[138:139], v[164:165]
	v_pk_fma_f32 v[144:145], v[140:141], v[166:167], v[144:145]
	v_add_f32 v146, v144, v145
	ds_read_b128 v[208:211], v5 offset:27648
	ds_read_b128 v[212:215], v5 offset:27904
	ds_read_b128 v[216:219], v5 offset:28160
	ds_read_b128 v[220:223], v5 offset:28416
	ds_read_b128 v[224:227], v5 offset:28672
	ds_read_b32 v228, v9 offset:27648
	v_add_f32_dpp v146, v146, v146 quad_perm:[1,0,3,2] row_mask:0xf bank_mask:0xf bound_ctrl:1
	v_pk_mul_f32 v[246:247], v[138:139], v[246:247]
	v_pk_fma_f32 v[246:247], v[140:141], v[248:249], v[246:247]
	v_add_f32_dpp v146, v146, v146 quad_perm:[2,3,0,1] row_mask:0xf bank_mask:0xf bound_ctrl:1
	v_add_f32 v163, v246, v247
	v_pk_mul_f32 v[176:177], v[176:177], v[184:185] op_sel_hi:[1,0]
	v_add_f32_dpp v146, v146, v146 row_half_mirror row_mask:0xf bank_mask:0xf bound_ctrl:1
	v_pk_mul_f32 v[178:179], v[178:179], v[184:185] op_sel_hi:[1,0]
	s_waitcnt lgkmcnt(6)
	v_add_f32_dpp v146, v146, v146 row_mirror row_mask:0xf bank_mask:0xf bound_ctrl:1
	v_pk_fma_f32 v[176:177], v[146:147], v[168:169], v[176:177] op_sel_hi:[0,1,1] neg_lo:[1,0,0] neg_hi:[1,0,0]
	v_pk_fma_f32 v[178:179], v[146:147], v[170:171], v[178:179] op_sel_hi:[0,1,1] neg_lo:[1,0,0] neg_hi:[1,0,0]
	v_pk_fma_f32 v[138:139], v[138:139], v[172:173], v[176:177]
	v_pk_fma_f32 v[140:141], v[140:141], v[174:175], v[178:179]
	v_pk_mul_f32 v[144:145], v[138:139], v[186:187]
	v_pk_fma_f32 v[144:145], v[140:141], v[188:189], v[144:145]
	v_add_f32 v146, v144, v145
	v_add_f32_dpp v230, v148, v148 row_mirror row_mask:0xf bank_mask:0x3 bound_ctrl:1
	v_add_f32_dpp v230, v156, v156 row_mirror row_mask:0xf bank_mask:0xc bound_ctrl:1
	v_add_f32_dpp v231, v149, v149 row_mirror row_mask:0xf bank_mask:0x3 bound_ctrl:1
	v_add_f32_dpp v231, v157, v157 row_mirror row_mask:0xf bank_mask:0xc bound_ctrl:1
	v_add_f32_dpp v232, v150, v150 row_mirror row_mask:0xf bank_mask:0x3 bound_ctrl:1
	v_add_f32_dpp v232, v158, v158 row_mirror row_mask:0xf bank_mask:0xc bound_ctrl:1
	v_add_f32_dpp v233, v151, v151 row_mirror row_mask:0xf bank_mask:0x3 bound_ctrl:1
	v_add_f32_dpp v233, v159, v159 row_mirror row_mask:0xf bank_mask:0xc bound_ctrl:1
	v_add_f32_dpp v234, v152, v152 row_mirror row_mask:0xf bank_mask:0x3 bound_ctrl:1
	v_add_f32_dpp v234, v160, v160 row_mirror row_mask:0xf bank_mask:0xc bound_ctrl:1
	v_add_f32_dpp v235, v153, v153 row_mirror row_mask:0xf bank_mask:0x3 bound_ctrl:1
	v_add_f32_dpp v235, v161, v161 row_mirror row_mask:0xf bank_mask:0xc bound_ctrl:1
	v_add_f32_dpp v236, v154, v154 row_mirror row_mask:0xf bank_mask:0x3 bound_ctrl:1
	v_add_f32_dpp v236, v162, v162 row_mirror row_mask:0xf bank_mask:0xc bound_ctrl:1
	v_add_f32_dpp v237, v155, v155 row_mirror row_mask:0xf bank_mask:0x3 bound_ctrl:1
	v_add_f32_dpp v237, v163, v163 row_mirror row_mask:0xf bank_mask:0xc bound_ctrl:1
	v_add_f32_dpp v238, v230, v230 row_half_mirror row_mask:0xf bank_mask:0x5 bound_ctrl:1
	v_add_f32_dpp v238, v234, v234 row_half_mirror row_mask:0xf bank_mask:0xa bound_ctrl:1
	v_add_f32_dpp v239, v231, v231 row_half_mirror row_mask:0xf bank_mask:0x5 bound_ctrl:1
	v_add_f32_dpp v239, v235, v235 row_half_mirror row_mask:0xf bank_mask:0xa bound_ctrl:1
	v_add_f32_dpp v240, v232, v232 row_half_mirror row_mask:0xf bank_mask:0x5 bound_ctrl:1
	v_add_f32_dpp v240, v236, v236 row_half_mirror row_mask:0xf bank_mask:0xa bound_ctrl:1
	v_add_f32_dpp v241, v233, v233 row_half_mirror row_mask:0xf bank_mask:0x5 bound_ctrl:1
	v_add_f32_dpp v241, v237, v237 row_half_mirror row_mask:0xf bank_mask:0xa bound_ctrl:1
	s_mov_b32 vcc_lo, 0xcccccccc
	s_mov_b32 vcc_hi, 0xcccccccc
	v_cndmask_b32 v244, v240, v238, vcc
	v_cndmask_b32 v245, v241, v239, vcc
	v_cndmask_b32 v242, v238, v240, vcc
	v_cndmask_b32 v243, v239, v241, vcc
	v_add_f32_dpp v242, v244, v242 quad_perm:[2,3,0,1] row_mask:0xf bank_mask:0xf bound_ctrl:1
	v_add_f32_dpp v243, v245, v243 quad_perm:[2,3,0,1] row_mask:0xf bank_mask:0xf bound_ctrl:1
	s_mov_b32 vcc_lo, 0xaaaaaaaa
	s_mov_b32 vcc_hi, 0xaaaaaaaa
	v_cndmask_b32 v244, v243, v242, vcc
	v_cndmask_b32 v245, v242, v243, vcc
	s_nop 0
	v_add_f32_dpp v18, v244, v245 quad_perm:[1,0,3,2] row_mask:0xf bank_mask:0xf bound_ctrl:1
	ds_read_b128 v[230:233], v5 offset:29184
	ds_read_b128 v[234:237], v5 offset:29440
	ds_read_b128 v[238:241], v5 offset:29696
	ds_read_b128 v[242:245], v5 offset:29952
	ds_read_b128 v[246:249], v5 offset:30208
	ds_read_b32 v250, v9 offset:29184
	v_add_f32_dpp v146, v146, v146 quad_perm:[1,0,3,2] row_mask:0xf bank_mask:0xf bound_ctrl:1
	v_pk_mul_f32 v[180:181], v[138:139], v[180:181]
	v_pk_fma_f32 v[180:181], v[140:141], v[182:183], v[180:181]
	v_add_f32_dpp v146, v146, v146 quad_perm:[2,3,0,1] row_mask:0xf bank_mask:0xf bound_ctrl:1
	v_add_f32 v148, v180, v181
	v_pk_mul_f32 v[198:199], v[198:199], v[206:207] op_sel_hi:[1,0]
	v_add_f32_dpp v146, v146, v146 row_half_mirror row_mask:0xf bank_mask:0xf bound_ctrl:1
	v_pk_mul_f32 v[200:201], v[200:201], v[206:207] op_sel_hi:[1,0]
	s_waitcnt lgkmcnt(6)
	v_add_f32_dpp v146, v146, v146 row_mirror row_mask:0xf bank_mask:0xf bound_ctrl:1
	v_pk_fma_f32 v[198:199], v[146:147], v[190:191], v[198:199] op_sel_hi:[0,1,1] neg_lo:[1,0,0] neg_hi:[1,0,0]
	v_pk_fma_f32 v[200:201], v[146:147], v[192:193], v[200:201] op_sel_hi:[0,1,1] neg_lo:[1,0,0] neg_hi:[1,0,0]
	v_pk_fma_f32 v[138:139], v[138:139], v[194:195], v[198:199]
	v_pk_fma_f32 v[140:141], v[140:141], v[196:197], v[200:201]
	v_pk_mul_f32 v[144:145], v[138:139], v[208:209]
	v_pk_fma_f32 v[144:145], v[140:141], v[210:211], v[144:145]
	v_add_f32 v146, v144, v145
	ds_read_b128 v[164:167], v5 offset:30720
	ds_read_b128 v[168:171], v5 offset:30976
	ds_read_b128 v[172:175], v5 offset:31232
	ds_read_b128 v[176:179], v5 offset:31488
	ds_read_b128 v[180:183], v5 offset:31744
	ds_read_b32 v184, v9 offset:30720
	v_add_f32_dpp v146, v146, v146 quad_perm:[1,0,3,2] row_mask:0xf bank_mask:0xf bound_ctrl:1
	v_pk_mul_f32 v[202:203], v[138:139], v[202:203]
	v_pk_fma_f32 v[202:203], v[140:141], v[204:205], v[202:203]
	v_add_f32_dpp v146, v146, v146 quad_perm:[2,3,0,1] row_mask:0xf bank_mask:0xf bound_ctrl:1
	v_add_f32 v149, v202, v203
	v_pk_mul_f32 v[220:221], v[220:221], v[228:229] op_sel_hi:[1,0]
	v_add_f32_dpp v146, v146, v146 row_half_mirror row_mask:0xf bank_mask:0xf bound_ctrl:1
	v_pk_mul_f32 v[222:223], v[222:223], v[228:229] op_sel_hi:[1,0]
	s_waitcnt lgkmcnt(6)
	v_add_f32_dpp v146, v146, v146 row_mirror row_mask:0xf bank_mask:0xf bound_ctrl:1
	v_pk_fma_f32 v[220:221], v[146:147], v[212:213], v[220:221] op_sel_hi:[0,1,1] neg_lo:[1,0,0] neg_hi:[1,0,0]
	v_pk_fma_f32 v[222:223], v[146:147], v[214:215], v[222:223] op_sel_hi:[0,1,1] neg_lo:[1,0,0] neg_hi:[1,0,0]
	v_pk_fma_f32 v[138:139], v[138:139], v[216:217], v[220:221]
	v_pk_fma_f32 v[140:141], v[140:141], v[218:219], v[222:223]
	v_pk_mul_f32 v[144:145], v[138:139], v[230:231]
	v_pk_fma_f32 v[144:145], v[140:141], v[232:233], v[144:145]
	v_add_f32 v146, v144, v145
	ds_read_b128 v[186:189], v5 offset:32256
	ds_read_b128 v[190:193], v5 offset:32512
	ds_read_b128 v[194:197], v5 offset:32768
	ds_read_b128 v[198:201], v5 offset:33024
	ds_read_b128 v[202:205], v5 offset:33280
	ds_read_b32 v206, v9 offset:32256
	v_add_f32_dpp v146, v146, v146 quad_perm:[1,0,3,2] row_mask:0xf bank_mask:0xf bound_ctrl:1
	v_pk_mul_f32 v[224:225], v[138:139], v[224:225]
	v_pk_fma_f32 v[224:225], v[140:141], v[226:227], v[224:225]
	v_add_f32_dpp v146, v146, v146 quad_perm:[2,3,0,1] row_mask:0xf bank_mask:0xf bound_ctrl:1
	v_add_f32 v150, v224, v225
	v_pk_mul_f32 v[242:243], v[242:243], v[250:251] op_sel_hi:[1,0]
	v_add_f32_dpp v146, v146, v146 row_half_mirror row_mask:0xf bank_mask:0xf bound_ctrl:1
	v_pk_mul_f32 v[244:245], v[244:245], v[250:251] op_sel_hi:[1,0]
	s_waitcnt lgkmcnt(6)
	v_add_f32_dpp v146, v146, v146 row_mirror row_mask:0xf bank_mask:0xf bound_ctrl:1
	v_pk_fma_f32 v[242:243], v[146:147], v[234:235], v[242:243] op_sel_hi:[0,1,1] neg_lo:[1,0,0] neg_hi:[1,0,0]
	v_pk_fma_f32 v[244:245], v[146:147], v[236:237], v[244:245] op_sel_hi:[0,1,1] neg_lo:[1,0,0] neg_hi:[1,0,0]
	v_pk_fma_f32 v[138:139], v[138:139], v[238:239], v[242:243]
	v_pk_fma_f32 v[140:141], v[140:141], v[240:241], v[244:245]
	v_pk_mul_f32 v[144:145], v[138:139], v[164:165]
	v_pk_fma_f32 v[144:145], v[140:141], v[166:167], v[144:145]
	v_add_f32 v146, v144, v145
	ds_read_b128 v[208:211], v5 offset:33792
	ds_read_b128 v[212:215], v5 offset:34048
	ds_read_b128 v[216:219], v5 offset:34304
	ds_read_b128 v[220:223], v5 offset:34560
	ds_read_b128 v[224:227], v5 offset:34816
	ds_read_b32 v228, v9 offset:33792
	v_add_f32_dpp v146, v146, v146 quad_perm:[1,0,3,2] row_mask:0xf bank_mask:0xf bound_ctrl:1
	v_pk_mul_f32 v[246:247], v[138:139], v[246:247]
	v_pk_fma_f32 v[246:247], v[140:141], v[248:249], v[246:247]
	v_add_f32_dpp v146, v146, v146 quad_perm:[2,3,0,1] row_mask:0xf bank_mask:0xf bound_ctrl:1
	v_add_f32 v151, v246, v247
	v_pk_mul_f32 v[176:177], v[176:177], v[184:185] op_sel_hi:[1,0]
	v_add_f32_dpp v146, v146, v146 row_half_mirror row_mask:0xf bank_mask:0xf bound_ctrl:1
	v_pk_mul_f32 v[178:179], v[178:179], v[184:185] op_sel_hi:[1,0]
	s_waitcnt lgkmcnt(6)
	v_add_f32_dpp v146, v146, v146 row_mirror row_mask:0xf bank_mask:0xf bound_ctrl:1
	v_pk_fma_f32 v[176:177], v[146:147], v[168:169], v[176:177] op_sel_hi:[0,1,1] neg_lo:[1,0,0] neg_hi:[1,0,0]
	v_pk_fma_f32 v[178:179], v[146:147], v[170:171], v[178:179] op_sel_hi:[0,1,1] neg_lo:[1,0,0] neg_hi:[1,0,0]
	v_pk_fma_f32 v[138:139], v[138:139], v[172:173], v[176:177]
	v_pk_fma_f32 v[140:141], v[140:141], v[174:175], v[178:179]
	v_pk_mul_f32 v[144:145], v[138:139], v[186:187]
	v_pk_fma_f32 v[144:145], v[140:141], v[188:189], v[144:145]
	v_add_f32 v146, v144, v145
	ds_read_b128 v[230:233], v5 offset:35328
	ds_read_b128 v[234:237], v5 offset:35584
	ds_read_b128 v[238:241], v5 offset:35840
	ds_read_b128 v[242:245], v5 offset:36096
	ds_read_b128 v[246:249], v5 offset:36352
	ds_read_b32 v250, v9 offset:35328
	v_add_f32_dpp v146, v146, v146 quad_perm:[1,0,3,2] row_mask:0xf bank_mask:0xf bound_ctrl:1
	v_pk_mul_f32 v[180:181], v[138:139], v[180:181]
	v_pk_fma_f32 v[180:181], v[140:141], v[182:183], v[180:181]
	v_add_f32_dpp v146, v146, v146 quad_perm:[2,3,0,1] row_mask:0xf bank_mask:0xf bound_ctrl:1
	v_add_f32 v152, v180, v181
	v_pk_mul_f32 v[198:199], v[198:199], v[206:207] op_sel_hi:[1,0]
	v_add_f32_dpp v146, v146, v146 row_half_mirror row_mask:0xf bank_mask:0xf bound_ctrl:1
	v_pk_mul_f32 v[200:201], v[200:201], v[206:207] op_sel_hi:[1,0]
	s_waitcnt lgkmcnt(6)
	v_add_f32_dpp v146, v146, v146 row_mirror row_mask:0xf bank_mask:0xf bound_ctrl:1
	v_pk_fma_f32 v[198:199], v[146:147], v[190:191], v[198:199] op_sel_hi:[0,1,1] neg_lo:[1,0,0] neg_hi:[1,0,0]
	v_pk_fma_f32 v[200:201], v[146:147], v[192:193], v[200:201] op_sel_hi:[0,1,1] neg_lo:[1,0,0] neg_hi:[1,0,0]
	v_pk_fma_f32 v[138:139], v[138:139], v[194:195], v[198:199]
	v_pk_fma_f32 v[140:141], v[140:141], v[196:197], v[200:201]
	v_pk_mul_f32 v[144:145], v[138:139], v[208:209]
	v_pk_fma_f32 v[144:145], v[140:141], v[210:211], v[144:145]
	v_add_f32 v146, v144, v145
	ds_read_b128 v[164:167], v5 offset:36864
	ds_read_b128 v[168:171], v5 offset:37120
	ds_read_b128 v[172:175], v5 offset:37376
	ds_read_b128 v[176:179], v5 offset:37632
	ds_read_b128 v[180:183], v5 offset:37888
	ds_read_b32 v184, v9 offset:36864
	v_add_f32_dpp v146, v146, v146 quad_perm:[1,0,3,2] row_mask:0xf bank_mask:0xf bound_ctrl:1
	v_pk_mul_f32 v[202:203], v[138:139], v[202:203]
	v_pk_fma_f32 v[202:203], v[140:141], v[204:205], v[202:203]
	v_add_f32_dpp v146, v146, v146 quad_perm:[2,3,0,1] row_mask:0xf bank_mask:0xf bound_ctrl:1
	v_add_f32 v153, v202, v203
	v_pk_mul_f32 v[220:221], v[220:221], v[228:229] op_sel_hi:[1,0]
	v_add_f32_dpp v146, v146, v146 row_half_mirror row_mask:0xf bank_mask:0xf bound_ctrl:1
	v_pk_mul_f32 v[222:223], v[222:223], v[228:229] op_sel_hi:[1,0]
	s_waitcnt lgkmcnt(6)
	v_add_f32_dpp v146, v146, v146 row_mirror row_mask:0xf bank_mask:0xf bound_ctrl:1
	v_pk_fma_f32 v[220:221], v[146:147], v[212:213], v[220:221] op_sel_hi:[0,1,1] neg_lo:[1,0,0] neg_hi:[1,0,0]
	v_pk_fma_f32 v[222:223], v[146:147], v[214:215], v[222:223] op_sel_hi:[0,1,1] neg_lo:[1,0,0] neg_hi:[1,0,0]
	v_pk_fma_f32 v[138:139], v[138:139], v[216:217], v[220:221]
	v_pk_fma_f32 v[140:141], v[140:141], v[218:219], v[222:223]
	v_pk_mul_f32 v[144:145], v[138:139], v[230:231]
	v_pk_fma_f32 v[144:145], v[140:141], v[232:233], v[144:145]
	v_add_f32 v146, v144, v145
	ds_read_b128 v[186:189], v5 offset:38400
	ds_read_b128 v[190:193], v5 offset:38656
	ds_read_b128 v[194:197], v5 offset:38912
	ds_read_b128 v[198:201], v5 offset:39168
	ds_read_b128 v[202:205], v5 offset:39424
	ds_read_b32 v206, v9 offset:38400
	v_add_f32_dpp v146, v146, v146 quad_perm:[1,0,3,2] row_mask:0xf bank_mask:0xf bound_ctrl:1
	v_pk_mul_f32 v[224:225], v[138:139], v[224:225]
	v_pk_fma_f32 v[224:225], v[140:141], v[226:227], v[224:225]
	v_add_f32_dpp v146, v146, v146 quad_perm:[2,3,0,1] row_mask:0xf bank_mask:0xf bound_ctrl:1
	v_add_f32 v154, v224, v225
	v_pk_mul_f32 v[242:243], v[242:243], v[250:251] op_sel_hi:[1,0]
	v_add_f32_dpp v146, v146, v146 row_half_mirror row_mask:0xf bank_mask:0xf bound_ctrl:1
	v_pk_mul_f32 v[244:245], v[244:245], v[250:251] op_sel_hi:[1,0]
	s_waitcnt lgkmcnt(6)
	v_add_f32_dpp v146, v146, v146 row_mirror row_mask:0xf bank_mask:0xf bound_ctrl:1
	v_pk_fma_f32 v[242:243], v[146:147], v[234:235], v[242:243] op_sel_hi:[0,1,1] neg_lo:[1,0,0] neg_hi:[1,0,0]
	v_pk_fma_f32 v[244:245], v[146:147], v[236:237], v[244:245] op_sel_hi:[0,1,1] neg_lo:[1,0,0] neg_hi:[1,0,0]
	v_pk_fma_f32 v[138:139], v[138:139], v[238:239], v[242:243]
	v_pk_fma_f32 v[140:141], v[140:141], v[240:241], v[244:245]
	v_pk_mul_f32 v[144:145], v[138:139], v[164:165]
	v_pk_fma_f32 v[144:145], v[140:141], v[166:167], v[144:145]
	v_add_f32 v146, v144, v145
	ds_read_b128 v[208:211], v5 offset:39936
	ds_read_b128 v[212:215], v5 offset:40192
	ds_read_b128 v[216:219], v5 offset:40448
	ds_read_b128 v[220:223], v5 offset:40704
	ds_read_b128 v[224:227], v5 offset:40960
	ds_read_b32 v228, v9 offset:39936
	v_add_f32_dpp v146, v146, v146 quad_perm:[1,0,3,2] row_mask:0xf bank_mask:0xf bound_ctrl:1
	v_pk_mul_f32 v[246:247], v[138:139], v[246:247]
	v_pk_fma_f32 v[246:247], v[140:141], v[248:249], v[246:247]
	v_add_f32_dpp v146, v146, v146 quad_perm:[2,3,0,1] row_mask:0xf bank_mask:0xf bound_ctrl:1
	v_add_f32 v155, v246, v247
	v_pk_mul_f32 v[176:177], v[176:177], v[184:185] op_sel_hi:[1,0]
	v_add_f32_dpp v146, v146, v146 row_half_mirror row_mask:0xf bank_mask:0xf bound_ctrl:1
	v_pk_mul_f32 v[178:179], v[178:179], v[184:185] op_sel_hi:[1,0]
	s_waitcnt lgkmcnt(6)
	v_add_f32_dpp v146, v146, v146 row_mirror row_mask:0xf bank_mask:0xf bound_ctrl:1
	v_pk_fma_f32 v[176:177], v[146:147], v[168:169], v[176:177] op_sel_hi:[0,1,1] neg_lo:[1,0,0] neg_hi:[1,0,0]
	v_pk_fma_f32 v[178:179], v[146:147], v[170:171], v[178:179] op_sel_hi:[0,1,1] neg_lo:[1,0,0] neg_hi:[1,0,0]
	v_pk_fma_f32 v[138:139], v[138:139], v[172:173], v[176:177]
	v_pk_fma_f32 v[140:141], v[140:141], v[174:175], v[178:179]
	v_pk_mul_f32 v[144:145], v[138:139], v[186:187]
	v_pk_fma_f32 v[144:145], v[140:141], v[188:189], v[144:145]
	v_add_f32 v146, v144, v145
	ds_read_b128 v[230:233], v5 offset:41472
	ds_read_b128 v[234:237], v5 offset:41728
	ds_read_b128 v[238:241], v5 offset:41984
	ds_read_b128 v[242:245], v5 offset:42240
	ds_read_b128 v[246:249], v5 offset:42496
	ds_read_b32 v250, v9 offset:41472
	v_add_f32_dpp v146, v146, v146 quad_perm:[1,0,3,2] row_mask:0xf bank_mask:0xf bound_ctrl:1
	v_pk_mul_f32 v[180:181], v[138:139], v[180:181]
	v_pk_fma_f32 v[180:181], v[140:141], v[182:183], v[180:181]
	v_add_f32_dpp v146, v146, v146 quad_perm:[2,3,0,1] row_mask:0xf bank_mask:0xf bound_ctrl:1
	v_add_f32 v156, v180, v181
	v_pk_mul_f32 v[198:199], v[198:199], v[206:207] op_sel_hi:[1,0]
	v_add_f32_dpp v146, v146, v146 row_half_mirror row_mask:0xf bank_mask:0xf bound_ctrl:1
	v_pk_mul_f32 v[200:201], v[200:201], v[206:207] op_sel_hi:[1,0]
	s_waitcnt lgkmcnt(6)
	v_add_f32_dpp v146, v146, v146 row_mirror row_mask:0xf bank_mask:0xf bound_ctrl:1
	v_pk_fma_f32 v[198:199], v[146:147], v[190:191], v[198:199] op_sel_hi:[0,1,1] neg_lo:[1,0,0] neg_hi:[1,0,0]
	v_pk_fma_f32 v[200:201], v[146:147], v[192:193], v[200:201] op_sel_hi:[0,1,1] neg_lo:[1,0,0] neg_hi:[1,0,0]
	v_pk_fma_f32 v[138:139], v[138:139], v[194:195], v[198:199]
	v_pk_fma_f32 v[140:141], v[140:141], v[196:197], v[200:201]
	v_pk_mul_f32 v[144:145], v[138:139], v[208:209]
	v_pk_fma_f32 v[144:145], v[140:141], v[210:211], v[144:145]
	v_add_f32 v146, v144, v145
	ds_read_b128 v[164:167], v5 offset:43008
	ds_read_b128 v[168:171], v5 offset:43264
	ds_read_b128 v[172:175], v5 offset:43520
	ds_read_b128 v[176:179], v5 offset:43776
	ds_read_b128 v[180:183], v5 offset:44032
	ds_read_b32 v184, v9 offset:43008
	v_add_f32_dpp v146, v146, v146 quad_perm:[1,0,3,2] row_mask:0xf bank_mask:0xf bound_ctrl:1
	v_pk_mul_f32 v[202:203], v[138:139], v[202:203]
	v_pk_fma_f32 v[202:203], v[140:141], v[204:205], v[202:203]
	v_add_f32_dpp v146, v146, v146 quad_perm:[2,3,0,1] row_mask:0xf bank_mask:0xf bound_ctrl:1
	v_add_f32 v157, v202, v203
	v_pk_mul_f32 v[220:221], v[220:221], v[228:229] op_sel_hi:[1,0]
	v_add_f32_dpp v146, v146, v146 row_half_mirror row_mask:0xf bank_mask:0xf bound_ctrl:1
	v_pk_mul_f32 v[222:223], v[222:223], v[228:229] op_sel_hi:[1,0]
	s_waitcnt lgkmcnt(6)
	v_add_f32_dpp v146, v146, v146 row_mirror row_mask:0xf bank_mask:0xf bound_ctrl:1
	v_pk_fma_f32 v[220:221], v[146:147], v[212:213], v[220:221] op_sel_hi:[0,1,1] neg_lo:[1,0,0] neg_hi:[1,0,0]
	v_pk_fma_f32 v[222:223], v[146:147], v[214:215], v[222:223] op_sel_hi:[0,1,1] neg_lo:[1,0,0] neg_hi:[1,0,0]
	v_pk_fma_f32 v[138:139], v[138:139], v[216:217], v[220:221]
	v_pk_fma_f32 v[140:141], v[140:141], v[218:219], v[222:223]
	v_pk_mul_f32 v[144:145], v[138:139], v[230:231]
	v_pk_fma_f32 v[144:145], v[140:141], v[232:233], v[144:145]
	v_add_f32 v146, v144, v145
	ds_read_b128 v[186:189], v5 offset:44544
	ds_read_b128 v[190:193], v5 offset:44800
	ds_read_b128 v[194:197], v5 offset:45056
	ds_read_b128 v[198:201], v5 offset:45312
	ds_read_b128 v[202:205], v5 offset:45568
	ds_read_b32 v206, v9 offset:44544
	v_add_f32_dpp v146, v146, v146 quad_perm:[1,0,3,2] row_mask:0xf bank_mask:0xf bound_ctrl:1
	v_pk_mul_f32 v[224:225], v[138:139], v[224:225]
	v_pk_fma_f32 v[224:225], v[140:141], v[226:227], v[224:225]
	v_add_f32_dpp v146, v146, v146 quad_perm:[2,3,0,1] row_mask:0xf bank_mask:0xf bound_ctrl:1
	v_add_f32 v158, v224, v225
	v_pk_mul_f32 v[242:243], v[242:243], v[250:251] op_sel_hi:[1,0]
	v_add_f32_dpp v146, v146, v146 row_half_mirror row_mask:0xf bank_mask:0xf bound_ctrl:1
	v_pk_mul_f32 v[244:245], v[244:245], v[250:251] op_sel_hi:[1,0]
	s_waitcnt lgkmcnt(6)
	v_add_f32_dpp v146, v146, v146 row_mirror row_mask:0xf bank_mask:0xf bound_ctrl:1
	v_pk_fma_f32 v[242:243], v[146:147], v[234:235], v[242:243] op_sel_hi:[0,1,1] neg_lo:[1,0,0] neg_hi:[1,0,0]
	v_pk_fma_f32 v[244:245], v[146:147], v[236:237], v[244:245] op_sel_hi:[0,1,1] neg_lo:[1,0,0] neg_hi:[1,0,0]
	v_pk_fma_f32 v[138:139], v[138:139], v[238:239], v[242:243]
	v_pk_fma_f32 v[140:141], v[140:141], v[240:241], v[244:245]
	v_pk_mul_f32 v[144:145], v[138:139], v[164:165]
	v_pk_fma_f32 v[144:145], v[140:141], v[166:167], v[144:145]
	v_add_f32 v146, v144, v145
	ds_read_b128 v[208:211], v5 offset:46080
	ds_read_b128 v[212:215], v5 offset:46336
	ds_read_b128 v[216:219], v5 offset:46592
	ds_read_b128 v[220:223], v5 offset:46848
	ds_read_b128 v[224:227], v5 offset:47104
	ds_read_b32 v228, v9 offset:46080
	v_add_f32_dpp v146, v146, v146 quad_perm:[1,0,3,2] row_mask:0xf bank_mask:0xf bound_ctrl:1
	v_pk_mul_f32 v[246:247], v[138:139], v[246:247]
	v_pk_fma_f32 v[246:247], v[140:141], v[248:249], v[246:247]
	v_add_f32_dpp v146, v146, v146 quad_perm:[2,3,0,1] row_mask:0xf bank_mask:0xf bound_ctrl:1
	v_add_f32 v159, v246, v247
	v_pk_mul_f32 v[176:177], v[176:177], v[184:185] op_sel_hi:[1,0]
	v_add_f32_dpp v146, v146, v146 row_half_mirror row_mask:0xf bank_mask:0xf bound_ctrl:1
	v_pk_mul_f32 v[178:179], v[178:179], v[184:185] op_sel_hi:[1,0]
	s_waitcnt lgkmcnt(6)
	v_add_f32_dpp v146, v146, v146 row_mirror row_mask:0xf bank_mask:0xf bound_ctrl:1
	v_pk_fma_f32 v[176:177], v[146:147], v[168:169], v[176:177] op_sel_hi:[0,1,1] neg_lo:[1,0,0] neg_hi:[1,0,0]
	v_pk_fma_f32 v[178:179], v[146:147], v[170:171], v[178:179] op_sel_hi:[0,1,1] neg_lo:[1,0,0] neg_hi:[1,0,0]
	v_pk_fma_f32 v[138:139], v[138:139], v[172:173], v[176:177]
	v_pk_fma_f32 v[140:141], v[140:141], v[174:175], v[178:179]
	v_pk_mul_f32 v[144:145], v[138:139], v[186:187]
	v_pk_fma_f32 v[144:145], v[140:141], v[188:189], v[144:145]
	v_add_f32 v146, v144, v145
	ds_read_b128 v[230:233], v5 offset:47616
	ds_read_b128 v[234:237], v5 offset:47872
	ds_read_b128 v[238:241], v5 offset:48128
	ds_read_b128 v[242:245], v5 offset:48384
	ds_read_b128 v[246:249], v5 offset:48640
	ds_read_b32 v250, v9 offset:47616
	v_add_f32_dpp v146, v146, v146 quad_perm:[1,0,3,2] row_mask:0xf bank_mask:0xf bound_ctrl:1
	v_pk_mul_f32 v[180:181], v[138:139], v[180:181]
	v_pk_fma_f32 v[180:181], v[140:141], v[182:183], v[180:181]
	v_add_f32_dpp v146, v146, v146 quad_perm:[2,3,0,1] row_mask:0xf bank_mask:0xf bound_ctrl:1
	v_add_f32 v160, v180, v181
	v_pk_mul_f32 v[198:199], v[198:199], v[206:207] op_sel_hi:[1,0]
	v_add_f32_dpp v146, v146, v146 row_half_mirror row_mask:0xf bank_mask:0xf bound_ctrl:1
	v_pk_mul_f32 v[200:201], v[200:201], v[206:207] op_sel_hi:[1,0]
	s_waitcnt lgkmcnt(6)
	v_add_f32_dpp v146, v146, v146 row_mirror row_mask:0xf bank_mask:0xf bound_ctrl:1
	v_pk_fma_f32 v[198:199], v[146:147], v[190:191], v[198:199] op_sel_hi:[0,1,1] neg_lo:[1,0,0] neg_hi:[1,0,0]
	v_pk_fma_f32 v[200:201], v[146:147], v[192:193], v[200:201] op_sel_hi:[0,1,1] neg_lo:[1,0,0] neg_hi:[1,0,0]
	v_pk_fma_f32 v[138:139], v[138:139], v[194:195], v[198:199]
	v_pk_fma_f32 v[140:141], v[140:141], v[196:197], v[200:201]
	v_pk_mul_f32 v[144:145], v[138:139], v[208:209]
	v_pk_fma_f32 v[144:145], v[140:141], v[210:211], v[144:145]
	v_add_f32 v146, v144, v145
	s_nop 1
	v_add_f32_dpp v146, v146, v146 quad_perm:[1,0,3,2] row_mask:0xf bank_mask:0xf bound_ctrl:1
	v_pk_mul_f32 v[202:203], v[138:139], v[202:203]
	v_pk_fma_f32 v[202:203], v[140:141], v[204:205], v[202:203]
	v_add_f32_dpp v146, v146, v146 quad_perm:[2,3,0,1] row_mask:0xf bank_mask:0xf bound_ctrl:1
	v_add_f32 v161, v202, v203
	v_pk_mul_f32 v[220:221], v[220:221], v[228:229] op_sel_hi:[1,0]
	v_add_f32_dpp v146, v146, v146 row_half_mirror row_mask:0xf bank_mask:0xf bound_ctrl:1
	v_pk_mul_f32 v[222:223], v[222:223], v[228:229] op_sel_hi:[1,0]
	s_waitcnt lgkmcnt(0)
	v_add_f32_dpp v146, v146, v146 row_mirror row_mask:0xf bank_mask:0xf bound_ctrl:1
	v_pk_fma_f32 v[220:221], v[146:147], v[212:213], v[220:221] op_sel_hi:[0,1,1] neg_lo:[1,0,0] neg_hi:[1,0,0]
	v_pk_fma_f32 v[222:223], v[146:147], v[214:215], v[222:223] op_sel_hi:[0,1,1] neg_lo:[1,0,0] neg_hi:[1,0,0]
	v_pk_fma_f32 v[138:139], v[138:139], v[216:217], v[220:221]
	v_pk_fma_f32 v[140:141], v[140:141], v[218:219], v[222:223]
	v_pk_mul_f32 v[144:145], v[138:139], v[230:231]
	v_pk_fma_f32 v[144:145], v[140:141], v[232:233], v[144:145]
	v_add_f32 v146, v144, v145
	s_nop 1
	v_add_f32_dpp v146, v146, v146 quad_perm:[1,0,3,2] row_mask:0xf bank_mask:0xf bound_ctrl:1
	v_pk_mul_f32 v[224:225], v[138:139], v[224:225]
	v_pk_fma_f32 v[224:225], v[140:141], v[226:227], v[224:225]
	v_add_f32_dpp v146, v146, v146 quad_perm:[2,3,0,1] row_mask:0xf bank_mask:0xf bound_ctrl:1
	v_add_f32 v162, v224, v225
	v_pk_mul_f32 v[242:243], v[242:243], v[250:251] op_sel_hi:[1,0]
	v_add_f32_dpp v146, v146, v146 row_half_mirror row_mask:0xf bank_mask:0xf bound_ctrl:1
	v_pk_mul_f32 v[244:245], v[244:245], v[250:251] op_sel_hi:[1,0]
	s_nop 0
	v_add_f32_dpp v146, v146, v146 row_mirror row_mask:0xf bank_mask:0xf bound_ctrl:1
	v_pk_fma_f32 v[242:243], v[146:147], v[234:235], v[242:243] op_sel_hi:[0,1,1] neg_lo:[1,0,0] neg_hi:[1,0,0]
	v_pk_fma_f32 v[244:245], v[146:147], v[236:237], v[244:245] op_sel_hi:[0,1,1] neg_lo:[1,0,0] neg_hi:[1,0,0]
	v_pk_fma_f32 v[138:139], v[138:139], v[238:239], v[242:243]
	v_pk_fma_f32 v[140:141], v[140:141], v[240:241], v[244:245]
	v_pk_mul_f32 v[246:247], v[138:139], v[246:247]
	v_pk_fma_f32 v[246:247], v[140:141], v[248:249], v[246:247]
	v_add_f32 v163, v246, v247
	s_nop 0
	v_add_f32_dpp v230, v148, v148 row_mirror row_mask:0xf bank_mask:0x3 bound_ctrl:1
	v_add_f32_dpp v230, v156, v156 row_mirror row_mask:0xf bank_mask:0xc bound_ctrl:1
	v_add_f32_dpp v231, v149, v149 row_mirror row_mask:0xf bank_mask:0x3 bound_ctrl:1
	v_add_f32_dpp v231, v157, v157 row_mirror row_mask:0xf bank_mask:0xc bound_ctrl:1
	v_add_f32_dpp v232, v150, v150 row_mirror row_mask:0xf bank_mask:0x3 bound_ctrl:1
	v_add_f32_dpp v232, v158, v158 row_mirror row_mask:0xf bank_mask:0xc bound_ctrl:1
	v_add_f32_dpp v233, v151, v151 row_mirror row_mask:0xf bank_mask:0x3 bound_ctrl:1
	v_add_f32_dpp v233, v159, v159 row_mirror row_mask:0xf bank_mask:0xc bound_ctrl:1
	v_add_f32_dpp v234, v152, v152 row_mirror row_mask:0xf bank_mask:0x3 bound_ctrl:1
	v_add_f32_dpp v234, v160, v160 row_mirror row_mask:0xf bank_mask:0xc bound_ctrl:1
	v_add_f32_dpp v235, v153, v153 row_mirror row_mask:0xf bank_mask:0x3 bound_ctrl:1
	v_add_f32_dpp v235, v161, v161 row_mirror row_mask:0xf bank_mask:0xc bound_ctrl:1
	v_add_f32_dpp v236, v154, v154 row_mirror row_mask:0xf bank_mask:0x3 bound_ctrl:1
	v_add_f32_dpp v236, v162, v162 row_mirror row_mask:0xf bank_mask:0xc bound_ctrl:1
	v_add_f32_dpp v237, v155, v155 row_mirror row_mask:0xf bank_mask:0x3 bound_ctrl:1
	v_add_f32_dpp v237, v163, v163 row_mirror row_mask:0xf bank_mask:0xc bound_ctrl:1
	v_add_f32_dpp v238, v230, v230 row_half_mirror row_mask:0xf bank_mask:0x5 bound_ctrl:1
	v_add_f32_dpp v238, v234, v234 row_half_mirror row_mask:0xf bank_mask:0xa bound_ctrl:1
	v_add_f32_dpp v239, v231, v231 row_half_mirror row_mask:0xf bank_mask:0x5 bound_ctrl:1
	v_add_f32_dpp v239, v235, v235 row_half_mirror row_mask:0xf bank_mask:0xa bound_ctrl:1
	v_add_f32_dpp v240, v232, v232 row_half_mirror row_mask:0xf bank_mask:0x5 bound_ctrl:1
	v_add_f32_dpp v240, v236, v236 row_half_mirror row_mask:0xf bank_mask:0xa bound_ctrl:1
	v_add_f32_dpp v241, v233, v233 row_half_mirror row_mask:0xf bank_mask:0x5 bound_ctrl:1
	v_add_f32_dpp v241, v237, v237 row_half_mirror row_mask:0xf bank_mask:0xa bound_ctrl:1
	s_mov_b32 vcc_lo, 0xcccccccc
	s_mov_b32 vcc_hi, 0xcccccccc
	v_cndmask_b32 v244, v240, v238, vcc
	v_cndmask_b32 v245, v241, v239, vcc
	v_cndmask_b32 v242, v238, v240, vcc
	v_cndmask_b32 v243, v239, v241, vcc
	v_add_f32_dpp v242, v244, v242 quad_perm:[2,3,0,1] row_mask:0xf bank_mask:0xf bound_ctrl:1
	v_add_f32_dpp v243, v245, v243 quad_perm:[2,3,0,1] row_mask:0xf bank_mask:0xf bound_ctrl:1
	s_mov_b32 vcc_lo, 0xaaaaaaaa
	s_mov_b32 vcc_hi, 0xaaaaaaaa
	v_cndmask_b32 v244, v243, v242, vcc
	v_cndmask_b32 v245, v242, v243, vcc
	s_nop 0
	v_add_f32_dpp v19, v244, v245 quad_perm:[1,0,3,2] row_mask:0xf bank_mask:0xf bound_ctrl:1

; #define SCAN_BAR() asm volatile("s_barrier" ::: "memory")
; __device__ __forceinline__ void scan_unit(const Ctx& C0, const float* scn, int T, int quarter, const float* S0, float* Sout, unsigned char* obase, int mode) {
;     ...
;             if (mode == 0) { *(float*)(obase + (size_t)(k * 32 + q) * UPITCH_B + rl * 4) = osel0; *(float*)(obase + (size_t)(k * 32 + 16 + q) * UPITCH_B + rl * 4) = osel1; }
;             SCAN_BAR();
	v_lshl_add_u64 v[14:15], v[6:7], 0, s[0:1]
	v_add_co_u32_e32 v16, vcc, 0xfc29000, v14
	s_mov_b32 s8, 0xfc7f000
	s_nop 0
	v_addc_co_u32_e32 v17, vcc, 0, v15, vcc
	global_store_dword v[16:17], v18, off offset:768
	v_add_co_u32_e32 v16, vcc, 0xfc54000, v14
	s_add_u32 s0, s0, 0xac000
	s_nop 0
	v_addc_co_u32_e32 v17, vcc, 0, v15, vcc
	global_store_dword v[16:17], v19, off offset:768
	s_barrier
	ds_read_b128 v[164:167], v10 offset:0
	ds_read_b128 v[168:171], v10 offset:256
	ds_read_b128 v[172:175], v10 offset:512
	ds_read_b128 v[176:179], v10 offset:768
	ds_read_b128 v[180:183], v10 offset:1024
	ds_read_b32 v184, v11 offset:0
	ds_read_b128 v[186:189], v10 offset:1536
	ds_read_b128 v[190:193], v10 offset:1792
	ds_read_b128 v[194:197], v10 offset:2048
	ds_read_b128 v[198:201], v10 offset:2304
	ds_read_b128 v[202:205], v10 offset:2560
	ds_read_b32 v206, v11 offset:1536
	s_waitcnt lgkmcnt(6)
	v_pk_mul_f32 v[144:145], v[138:139], v[164:165]
	v_pk_fma_f32 v[144:145], v[140:141], v[166:167], v[144:145]
	v_add_f32 v146, v144, v145
	ds_read_b128 v[208:211], v10 offset:3072
	ds_read_b128 v[212:215], v10 offset:3328
	ds_read_b128 v[216:219], v10 offset:3584
	ds_read_b128 v[220:223], v10 offset:3840
	ds_read_b128 v[224:227], v10 offset:4096
	ds_read_b32 v228, v11 offset:3072
	v_add_f32_dpp v146, v146, v146 quad_perm:[1,0,3,2] row_mask:0xf bank_mask:0xf bound_ctrl:1
	s_nop 0
	s_nop 0
	v_add_f32_dpp v146, v146, v146 quad_perm:[2,3,0,1] row_mask:0xf bank_mask:0xf bound_ctrl:1
	s_nop 0
	v_pk_mul_f32 v[176:177], v[176:177], v[184:185] op_sel_hi:[1,0]
	v_add_f32_dpp v146, v146, v146 row_half_mirror row_mask:0xf bank_mask:0xf bound_ctrl:1
	v_pk_mul_f32 v[178:179], v[178:179], v[184:185] op_sel_hi:[1,0]
	s_waitcnt lgkmcnt(6)
	v_add_f32_dpp v146, v146, v146 row_mirror row_mask:0xf bank_mask:0xf bound_ctrl:1
	v_pk_fma_f32 v[176:177], v[146:147], v[168:169], v[176:177] op_sel_hi:[0,1,1] neg_lo:[1,0,0] neg_hi:[1,0,0]
	v_pk_fma_f32 v[178:179], v[146:147], v[170:171], v[178:179] op_sel_hi:[0,1,1] neg_lo:[1,0,0] neg_hi:[1,0,0]
	v_pk_fma_f32 v[138:139], v[138:139], v[172:173], v[176:177]
	v_pk_fma_f32 v[140:141], v[140:141], v[174:175], v[178:179]
	v_pk_mul_f32 v[144:145], v[138:139], v[186:187]
	v_pk_fma_f32 v[144:145], v[140:141], v[188:189], v[144:145]
	v_add_f32 v146, v144, v145
	ds_read_b128 v[230:233], v10 offset:4608
	ds_read_b128 v[234:237], v10 offset:4864
	ds_read_b128 v[238:241], v10 offset:5120
	ds_read_b128 v[242:245], v10 offset:5376
	ds_read_b128 v[246:249], v10 offset:5632
	ds_read_b32 v250, v11 offset:4608
	v_add_f32_dpp v146, v146, v146 quad_perm:[1,0,3,2] row_mask:0xf bank_mask:0xf bound_ctrl:1
	v_pk_mul_f32 v[180:181], v[138:139], v[180:181]
	v_pk_fma_f32 v[180:181], v[140:141], v[182:183], v[180:181]
	v_add_f32_dpp v146, v146, v146 quad_perm:[2,3,0,1] row_mask:0xf bank_mask:0xf bound_ctrl:1
	v_add_f32 v148, v180, v181
	v_pk_mul_f32 v[198:199], v[198:199], v[206:207] op_sel_hi:[1,0]
	v_add_f32_dpp v146, v146, v146 row_half_mirror row_mask:0xf bank_mask:0xf bound_ctrl:1
	v_pk_mul_f32 v[200:201], v[200:201], v[206:207] op_sel_hi:[1,0]
	s_waitcnt lgkmcnt(6)
	v_add_f32_dpp v146, v146, v146 row_mirror row_mask:0xf bank_mask:0xf bound_ctrl:1
	v_pk_fma_f32 v[198:199], v[146:147], v[190:191], v[198:199] op_sel_hi:[0,1,1] neg_lo:[1,0,0] neg_hi:[1,0,0]
	v_pk_fma_f32 v[200:201], v[146:147], v[192:193], v[200:201] op_sel_hi:[0,1,1] neg_lo:[1,0,0] neg_hi:[1,0,0]
	v_pk_fma_f32 v[138:139], v[138:139], v[194:195], v[198:199]
	v_pk_fma_f32 v[140:141], v[140:141], v[196:197], v[200:201]
	v_pk_mul_f32 v[144:145], v[138:139], v[208:209]
	v_pk_fma_f32 v[144:145], v[140:141], v[210:211], v[144:145]
	v_add_f32 v146, v144, v145
	ds_read_b128 v[164:167], v10 offset:6144
	ds_read_b128 v[168:171], v10 offset:6400
	ds_read_b128 v[172:175], v10 offset:6656
	ds_read_b128 v[176:179], v10 offset:6912
	ds_read_b128 v[180:183], v10 offset:7168
	ds_read_b32 v184, v11 offset:6144
	v_add_f32_dpp v146, v146, v146 quad_perm:[1,0,3,2] row_mask:0xf bank_mask:0xf bound_ctrl:1
	v_pk_mul_f32 v[202:203], v[138:139], v[202:203]
	v_pk_fma_f32 v[202:203], v[140:141], v[204:205], v[202:203]
	v_add_f32_dpp v146, v146, v146 quad_perm:[2,3,0,1] row_mask:0xf bank_mask:0xf bound_ctrl:1
	v_add_f32 v149, v202, v203
	v_pk_mul_f32 v[220:221], v[220:221], v[228:229] op_sel_hi:[1,0]
	v_add_f32_dpp v146, v146, v146 row_half_mirror row_mask:0xf bank_mask:0xf bound_ctrl:1
	v_pk_mul_f32 v[222:223], v[222:223], v[228:229] op_sel_hi:[1,0]
	s_waitcnt lgkmcnt(6)
	v_add_f32_dpp v146, v146, v146 row_mirror row_mask:0xf bank_mask:0xf bound_ctrl:1
	v_pk_fma_f32 v[220:221], v[146:147], v[212:213], v[220:221] op_sel_hi:[0,1,1] neg_lo:[1,0,0] neg_hi:[1,0,0]
	v_pk_fma_f32 v[222:223], v[146:147], v[214:215], v[222:223] op_sel_hi:[0,1,1] neg_lo:[1,0,0] neg_hi:[1,0,0]
	v_pk_fma_f32 v[138:139], v[138:139], v[216:217], v[220:221]
	v_pk_fma_f32 v[140:141], v[140:141], v[218:219], v[222:223]
	v_pk_mul_f32 v[144:145], v[138:139], v[230:231]
	v_pk_fma_f32 v[144:145], v[140:141], v[232:233], v[144:145]
	v_add_f32 v146, v144, v145
	ds_read_b128 v[186:189], v10 offset:7680
	ds_read_b128 v[190:193], v10 offset:7936
	ds_read_b128 v[194:197], v10 offset:8192
	ds_read_b128 v[198:201], v10 offset:8448
	ds_read_b128 v[202:205], v10 offset:8704
	ds_read_b32 v206, v11 offset:7680
	v_add_f32_dpp v146, v146, v146 quad_perm:[1,0,3,2] row_mask:0xf bank_mask:0xf bound_ctrl:1
	v_pk_mul_f32 v[224:225], v[138:139], v[224:225]
	v_pk_fma_f32 v[224:225], v[140:141], v[226:227], v[224:225]
	v_add_f32_dpp v146, v146, v146 quad_perm:[2,3,0,1] row_mask:0xf bank_mask:0xf bound_ctrl:1
	v_add_f32 v150, v224, v225
	v_pk_mul_f32 v[242:243], v[242:243], v[250:251] op_sel_hi:[1,0]
	v_add_f32_dpp v146, v146, v146 row_half_mirror row_mask:0xf bank_mask:0xf bound_ctrl:1
	v_pk_mul_f32 v[244:245], v[244:245], v[250:251] op_sel_hi:[1,0]
	s_waitcnt lgkmcnt(6)
	v_add_f32_dpp v146, v146, v146 row_mirror row_mask:0xf bank_mask:0xf bound_ctrl:1
	v_pk_fma_f32 v[242:243], v[146:147], v[234:235], v[242:243] op_sel_hi:[0,1,1] neg_lo:[1,0,0] neg_hi:[1,0,0]
	v_pk_fma_f32 v[244:245], v[146:147], v[236:237], v[244:245] op_sel_hi:[0,1,1] neg_lo:[1,0,0] neg_hi:[1,0,0]
	v_pk_fma_f32 v[138:139], v[138:139], v[238:239], v[242:243]
	v_pk_fma_f32 v[140:141], v[140:141], v[240:241], v[244:245]
	v_pk_mul_f32 v[144:145], v[138:139], v[164:165]
	v_pk_fma_f32 v[144:145], v[140:141], v[166:167], v[144:145]
	v_add_f32 v146, v144, v145
	ds_read_b128 v[208:211], v10 offset:9216
	ds_read_b128 v[212:215], v10 offset:9472
	ds_read_b128 v[216:219], v10 offset:9728
	ds_read_b128 v[220:223], v10 offset:9984
	ds_read_b128 v[224:227], v10 offset:10240
	ds_read_b32 v228, v11 offset:9216
	v_add_f32_dpp v146, v146, v146 quad_perm:[1,0,3,2] row_mask:0xf bank_mask:0xf bound_ctrl:1
	v_pk_mul_f32 v[246:247], v[138:139], v[246:247]
	v_pk_fma_f32 v[246:247], v[140:141], v[248:249], v[246:247]
	v_add_f32_dpp v146, v146, v146 quad_perm:[2,3,0,1] row_mask:0xf bank_mask:0xf bound_ctrl:1
	v_add_f32 v151, v246, v247
	v_pk_mul_f32 v[176:177], v[176:177], v[184:185] op_sel_hi:[1,0]
	v_add_f32_dpp v146, v146, v146 row_half_mirror row_mask:0xf bank_mask:0xf bound_ctrl:1
	v_pk_mul_f32 v[178:179], v[178:179], v[184:185] op_sel_hi:[1,0]
	s_waitcnt lgkmcnt(6)
	v_add_f32_dpp v146, v146, v146 row_mirror row_mask:0xf bank_mask:0xf bound_ctrl:1
	v_pk_fma_f32 v[176:177], v[146:147], v[168:169], v[176:177] op_sel_hi:[0,1,1] neg_lo:[1,0,0] neg_hi:[1,0,0]
	v_pk_fma_f32 v[178:179], v[146:147], v[170:171], v[178:179] op_sel_hi:[0,1,1] neg_lo:[1,0,0] neg_hi:[1,0,0]
	v_pk_fma_f32 v[138:139], v[138:139], v[172:173], v[176:177]
	v_pk_fma_f32 v[140:141], v[140:141], v[174:175], v[178:179]
	v_pk_mul_f32 v[144:145], v[138:139], v[186:187]
	v_pk_fma_f32 v[144:145], v[140:141], v[188:189], v[144:145]
	v_add_f32 v146, v144, v145
	ds_read_b128 v[230:233], v10 offset:10752
	ds_read_b128 v[234:237], v10 offset:11008
	ds_read_b128 v[238:241], v10 offset:11264
	ds_read_b128 v[242:245], v10 offset:11520
	ds_read_b128 v[246:249], v10 offset:11776
	ds_read_b32 v250, v11 offset:10752
	v_add_f32_dpp v146, v146, v146 quad_perm:[1,0,3,2] row_mask:0xf bank_mask:0xf bound_ctrl:1
	v_pk_mul_f32 v[180:181], v[138:139], v[180:181]
	v_pk_fma_f32 v[180:181], v[140:141], v[182:183], v[180:181]
	v_add_f32_dpp v146, v146, v146 quad_perm:[2,3,0,1] row_mask:0xf bank_mask:0xf bound_ctrl:1
	v_add_f32 v152, v180, v181
	v_pk_mul_f32 v[198:199], v[198:199], v[206:207] op_sel_hi:[1,0]
	v_add_f32_dpp v146, v146, v146 row_half_mirror row_mask:0xf bank_mask:0xf bound_ctrl:1
	v_pk_mul_f32 v[200:201], v[200:201], v[206:207] op_sel_hi:[1,0]
	s_waitcnt lgkmcnt(6)
	v_add_f32_dpp v146, v146, v146 row_mirror row_mask:0xf bank_mask:0xf bound_ctrl:1
	v_pk_fma_f32 v[198:199], v[146:147], v[190:191], v[198:199] op_sel_hi:[0,1,1] neg_lo:[1,0,0] neg_hi:[1,0,0]
	v_pk_fma_f32 v[200:201], v[146:147], v[192:193], v[200:201] op_sel_hi:[0,1,1] neg_lo:[1,0,0] neg_hi:[1,0,0]
	v_pk_fma_f32 v[138:139], v[138:139], v[194:195], v[198:199]
	v_pk_fma_f32 v[140:141], v[140:141], v[196:197], v[200:201]
	v_pk_mul_f32 v[144:145], v[138:139], v[208:209]
	v_pk_fma_f32 v[144:145], v[140:141], v[210:211], v[144:145]
	v_add_f32 v146, v144, v145
	ds_read_b128 v[164:167], v10 offset:12288
	ds_read_b128 v[168:171], v10 offset:12544
	ds_read_b128 v[172:175], v10 offset:12800
	ds_read_b128 v[176:179], v10 offset:13056
	ds_read_b128 v[180:183], v10 offset:13312
	ds_read_b32 v184, v11 offset:12288
	v_add_f32_dpp v146, v146, v146 quad_perm:[1,0,3,2] row_mask:0xf bank_mask:0xf bound_ctrl:1
	v_pk_mul_f32 v[202:203], v[138:139], v[202:203]
	v_pk_fma_f32 v[202:203], v[140:141], v[204:205], v[202:203]
	v_add_f32_dpp v146, v146, v146 quad_perm:[2,3,0,1] row_mask:0xf bank_mask:0xf bound_ctrl:1
	v_add_f32 v153, v202, v203
	v_pk_mul_f32 v[220:221], v[220:221], v[228:229] op_sel_hi:[1,0]
	v_add_f32_dpp v146, v146, v146 row_half_mirror row_mask:0xf bank_mask:0xf bound_ctrl:1
	v_pk_mul_f32 v[222:223], v[222:223], v[228:229] op_sel_hi:[1,0]
	s_waitcnt lgkmcnt(6)
	v_add_f32_dpp v146, v146, v146 row_mirror row_mask:0xf bank_mask:0xf bound_ctrl:1
	v_pk_fma_f32 v[220:221], v[146:147], v[212:213], v[220:221] op_sel_hi:[0,1,1] neg_lo:[1,0,0] neg_hi:[1,0,0]
	v_pk_fma_f32 v[222:223], v[146:147], v[214:215], v[222:223] op_sel_hi:[0,1,1] neg_lo:[1,0,0] neg_hi:[1,0,0]
	v_pk_fma_f32 v[138:139], v[138:139], v[216:217], v[220:221]
	v_pk_fma_f32 v[140:141], v[140:141], v[218:219], v[222:223]
	v_pk_mul_f32 v[144:145], v[138:139], v[230:231]
	v_pk_fma_f32 v[144:145], v[140:141], v[232:233], v[144:145]
	v_add_f32 v146, v144, v145
	ds_read_b128 v[186:189], v10 offset:13824
	ds_read_b128 v[190:193], v10 offset:14080
	ds_read_b128 v[194:197], v10 offset:14336
	ds_read_b128 v[198:201], v10 offset:14592
	ds_read_b128 v[202:205], v10 offset:14848
	ds_read_b32 v206, v11 offset:13824
	v_add_f32_dpp v146, v146, v146 quad_perm:[1,0,3,2] row_mask:0xf bank_mask:0xf bound_ctrl:1
	v_pk_mul_f32 v[224:225], v[138:139], v[224:225]
	v_pk_fma_f32 v[224:225], v[140:141], v[226:227], v[224:225]
	v_add_f32_dpp v146, v146, v146 quad_perm:[2,3,0,1] row_mask:0xf bank_mask:0xf bound_ctrl:1
	v_add_f32 v154, v224, v225
	v_pk_mul_f32 v[242:243], v[242:243], v[250:251] op_sel_hi:[1,0]
	v_add_f32_dpp v146, v146, v146 row_half_mirror row_mask:0xf bank_mask:0xf bound_ctrl:1
	v_pk_mul_f32 v[244:245], v[244:245], v[250:251] op_sel_hi:[1,0]
	s_waitcnt lgkmcnt(6)
	v_add_f32_dpp v146, v146, v146 row_mirror row_mask:0xf bank_mask:0xf bound_ctrl:1
	v_pk_fma_f32 v[242:243], v[146:147], v[234:235], v[242:243] op_sel_hi:[0,1,1] neg_lo:[1,0,0] neg_hi:[1,0,0]
	v_pk_fma_f32 v[244:245], v[146:147], v[236:237], v[244:245] op_sel_hi:[0,1,1] neg_lo:[1,0,0] neg_hi:[1,0,0]
	v_pk_fma_f32 v[138:139], v[138:139], v[238:239], v[242:243]
	v_pk_fma_f32 v[140:141], v[140:141], v[240:241], v[244:245]
	v_pk_mul_f32 v[144:145], v[138:139], v[164:165]
	v_pk_fma_f32 v[144:145], v[140:141], v[166:167], v[144:145]
	v_add_f32 v146, v144, v145
	ds_read_b128 v[208:211], v10 offset:15360
	ds_read_b128 v[212:215], v10 offset:15616
	ds_read_b128 v[216:219], v10 offset:15872
	ds_read_b128 v[220:223], v10 offset:16128
	ds_read_b128 v[224:227], v10 offset:16384
	ds_read_b32 v228, v11 offset:15360
	v_add_f32_dpp v146, v146, v146 quad_perm:[1,0,3,2] row_mask:0xf bank_mask:0xf bound_ctrl:1
	v_pk_mul_f32 v[246:247], v[138:139], v[246:247]
	v_pk_fma_f32 v[246:247], v[140:141], v[248:249], v[246:247]
	v_add_f32_dpp v146, v146, v146 quad_perm:[2,3,0,1] row_mask:0xf bank_mask:0xf bound_ctrl:1
	v_add_f32 v155, v246, v247
	v_pk_mul_f32 v[176:177], v[176:177], v[184:185] op_sel_hi:[1,0]
	v_add_f32_dpp v146, v146, v146 row_half_mirror row_mask:0xf bank_mask:0xf bound_ctrl:1
	v_pk_mul_f32 v[178:179], v[178:179], v[184:185] op_sel_hi:[1,0]
	s_waitcnt lgkmcnt(6)
	v_add_f32_dpp v146, v146, v146 row_mirror row_mask:0xf bank_mask:0xf bound_ctrl:1
	v_pk_fma_f32 v[176:177], v[146:147], v[168:169], v[176:177] op_sel_hi:[0,1,1] neg_lo:[1,0,0] neg_hi:[1,0,0]
	v_pk_fma_f32 v[178:179], v[146:147], v[170:171], v[178:179] op_sel_hi:[0,1,1] neg_lo:[1,0,0] neg_hi:[1,0,0]
	v_pk_fma_f32 v[138:139], v[138:139], v[172:173], v[176:177]
	v_pk_fma_f32 v[140:141], v[140:141], v[174:175], v[178:179]
	v_pk_mul_f32 v[144:145], v[138:139], v[186:187]
	v_pk_fma_f32 v[144:145], v[140:141], v[188:189], v[144:145]
	v_add_f32 v146, v144, v145
	ds_read_b128 v[230:233], v10 offset:16896
	ds_read_b128 v[234:237], v10 offset:17152
	ds_read_b128 v[238:241], v10 offset:17408
	ds_read_b128 v[242:245], v10 offset:17664
	ds_read_b128 v[246:249], v10 offset:17920
	ds_read_b32 v250, v11 offset:16896
	v_add_f32_dpp v146, v146, v146 quad_perm:[1,0,3,2] row_mask:0xf bank_mask:0xf bound_ctrl:1
	v_pk_mul_f32 v[180:181], v[138:139], v[180:181]
	v_pk_fma_f32 v[180:181], v[140:141], v[182:183], v[180:181]
	v_add_f32_dpp v146, v146, v146 quad_perm:[2,3,0,1] row_mask:0xf bank_mask:0xf bound_ctrl:1
	v_add_f32 v156, v180, v181
	v_pk_mul_f32 v[198:199], v[198:199], v[206:207] op_sel_hi:[1,0]
	v_add_f32_dpp v146, v146, v146 row_half_mirror row_mask:0xf bank_mask:0xf bound_ctrl:1
	v_pk_mul_f32 v[200:201], v[200:201], v[206:207] op_sel_hi:[1,0]
	s_waitcnt lgkmcnt(6)
	v_add_f32_dpp v146, v146, v146 row_mirror row_mask:0xf bank_mask:0xf bound_ctrl:1
	v_pk_fma_f32 v[198:199], v[146:147], v[190:191], v[198:199] op_sel_hi:[0,1,1] neg_lo:[1,0,0] neg_hi:[1,0,0]
	v_pk_fma_f32 v[200:201], v[146:147], v[192:193], v[200:201] op_sel_hi:[0,1,1] neg_lo:[1,0,0] neg_hi:[1,0,0]
	v_pk_fma_f32 v[138:139], v[138:139], v[194:195], v[198:199]
	v_pk_fma_f32 v[140:141], v[140:141], v[196:197], v[200:201]
	v_pk_mul_f32 v[144:145], v[138:139], v[208:209]
	v_pk_fma_f32 v[144:145], v[140:141], v[210:211], v[144:145]
	v_add_f32 v146, v144, v145
	ds_read_b128 v[164:167], v10 offset:18432
	ds_read_b128 v[168:171], v10 offset:18688
	ds_read_b128 v[172:175], v10 offset:18944
	ds_read_b128 v[176:179], v10 offset:19200
	ds_read_b128 v[180:183], v10 offset:19456
	ds_read_b32 v184, v11 offset:18432
	v_add_f32_dpp v146, v146, v146 quad_perm:[1,0,3,2] row_mask:0xf bank_mask:0xf bound_ctrl:1
	v_pk_mul_f32 v[202:203], v[138:139], v[202:203]
	v_pk_fma_f32 v[202:203], v[140:141], v[204:205], v[202:203]
	v_add_f32_dpp v146, v146, v146 quad_perm:[2,3,0,1] row_mask:0xf bank_mask:0xf bound_ctrl:1
	v_add_f32 v157, v202, v203
	v_pk_mul_f32 v[220:221], v[220:221], v[228:229] op_sel_hi:[1,0]
	v_add_f32_dpp v146, v146, v146 row_half_mirror row_mask:0xf bank_mask:0xf bound_ctrl:1
	v_pk_mul_f32 v[222:223], v[222:223], v[228:229] op_sel_hi:[1,0]
	s_waitcnt lgkmcnt(6)
	v_add_f32_dpp v146, v146, v146 row_mirror row_mask:0xf bank_mask:0xf bound_ctrl:1
	v_pk_fma_f32 v[220:221], v[146:147], v[212:213], v[220:221] op_sel_hi:[0,1,1] neg_lo:[1,0,0] neg_hi:[1,0,0]
	v_pk_fma_f32 v[222:223], v[146:147], v[214:215], v[222:223] op_sel_hi:[0,1,1] neg_lo:[1,0,0] neg_hi:[1,0,0]
	v_pk_fma_f32 v[138:139], v[138:139], v[216:217], v[220:221]
	v_pk_fma_f32 v[140:141], v[140:141], v[218:219], v[222:223]
	v_pk_mul_f32 v[144:145], v[138:139], v[230:231]
	v_pk_fma_f32 v[144:145], v[140:141], v[232:233], v[144:145]
	v_add_f32 v146, v144, v145
	ds_read_b128 v[186:189], v10 offset:19968
	ds_read_b128 v[190:193], v10 offset:20224
	ds_read_b128 v[194:197], v10 offset:20480
	ds_read_b128 v[198:201], v10 offset:20736
	ds_read_b128 v[202:205], v10 offset:20992
	ds_read_b32 v206, v11 offset:19968
	v_add_f32_dpp v146, v146, v146 quad_perm:[1,0,3,2] row_mask:0xf bank_mask:0xf bound_ctrl:1
	v_pk_mul_f32 v[224:225], v[138:139], v[224:225]
	v_pk_fma_f32 v[224:225], v[140:141], v[226:227], v[224:225]
	v_add_f32_dpp v146, v146, v146 quad_perm:[2,3,0,1] row_mask:0xf bank_mask:0xf bound_ctrl:1
	v_add_f32 v158, v224, v225
	v_pk_mul_f32 v[242:243], v[242:243], v[250:251] op_sel_hi:[1,0]
	v_add_f32_dpp v146, v146, v146 row_half_mirror row_mask:0xf bank_mask:0xf bound_ctrl:1
	v_pk_mul_f32 v[244:245], v[244:245], v[250:251] op_sel_hi:[1,0]
	s_waitcnt lgkmcnt(6)
	v_add_f32_dpp v146, v146, v146 row_mirror row_mask:0xf bank_mask:0xf bound_ctrl:1
	v_pk_fma_f32 v[242:243], v[146:147], v[234:235], v[242:243] op_sel_hi:[0,1,1] neg_lo:[1,0,0] neg_hi:[1,0,0]
	v_pk_fma_f32 v[244:245], v[146:147], v[236:237], v[244:245] op_sel_hi:[0,1,1] neg_lo:[1,0,0] neg_hi:[1,0,0]
	v_pk_fma_f32 v[138:139], v[138:139], v[238:239], v[242:243]
	v_pk_fma_f32 v[140:141], v[140:141], v[240:241], v[244:245]
	v_pk_mul_f32 v[144:145], v[138:139], v[164:165]
	v_pk_fma_f32 v[144:145], v[140:141], v[166:167], v[144:145]
	v_add_f32 v146, v144, v145
	ds_read_b128 v[208:211], v10 offset:21504
	ds_read_b128 v[212:215], v10 offset:21760
	ds_read_b128 v[216:219], v10 offset:22016
	ds_read_b128 v[220:223], v10 offset:22272
	ds_read_b128 v[224:227], v10 offset:22528
	ds_read_b32 v228, v11 offset:21504
	v_add_f32_dpp v146, v146, v146 quad_perm:[1,0,3,2] row_mask:0xf bank_mask:0xf bound_ctrl:1
	v_pk_mul_f32 v[246:247], v[138:139], v[246:247]
	v_pk_fma_f32 v[246:247], v[140:141], v[248:249], v[246:247]
	v_add_f32_dpp v146, v146, v146 quad_perm:[2,3,0,1] row_mask:0xf bank_mask:0xf bound_ctrl:1
	v_add_f32 v159, v246, v247
	v_pk_mul_f32 v[176:177], v[176:177], v[184:185] op_sel_hi:[1,0]
	v_add_f32_dpp v146, v146, v146 row_half_mirror row_mask:0xf bank_mask:0xf bound_ctrl:1
	v_pk_mul_f32 v[178:179], v[178:179], v[184:185] op_sel_hi:[1,0]
	s_waitcnt lgkmcnt(6)
	v_add_f32_dpp v146, v146, v146 row_mirror row_mask:0xf bank_mask:0xf bound_ctrl:1
	v_pk_fma_f32 v[176:177], v[146:147], v[168:169], v[176:177] op_sel_hi:[0,1,1] neg_lo:[1,0,0] neg_hi:[1,0,0]
	v_pk_fma_f32 v[178:179], v[146:147], v[170:171], v[178:179] op_sel_hi:[0,1,1] neg_lo:[1,0,0] neg_hi:[1,0,0]
	v_pk_fma_f32 v[138:139], v[138:139], v[172:173], v[176:177]
	v_pk_fma_f32 v[140:141], v[140:141], v[174:175], v[178:179]
	v_pk_mul_f32 v[144:145], v[138:139], v[186:187]
	v_pk_fma_f32 v[144:145], v[140:141], v[188:189], v[144:145]
	v_add_f32 v146, v144, v145
	ds_read_b128 v[230:233], v10 offset:23040
	ds_read_b128 v[234:237], v10 offset:23296
	ds_read_b128 v[238:241], v10 offset:23552
	ds_read_b128 v[242:245], v10 offset:23808
	ds_read_b128 v[246:249], v10 offset:24064
	ds_read_b32 v250, v11 offset:23040
	v_add_f32_dpp v146, v146, v146 quad_perm:[1,0,3,2] row_mask:0xf bank_mask:0xf bound_ctrl:1
	v_pk_mul_f32 v[180:181], v[138:139], v[180:181]
	v_pk_fma_f32 v[180:181], v[140:141], v[182:183], v[180:181]
	v_add_f32_dpp v146, v146, v146 quad_perm:[2,3,0,1] row_mask:0xf bank_mask:0xf bound_ctrl:1
	v_add_f32 v160, v180, v181
	v_pk_mul_f32 v[198:199], v[198:199], v[206:207] op_sel_hi:[1,0]
	v_add_f32_dpp v146, v146, v146 row_half_mirror row_mask:0xf bank_mask:0xf bound_ctrl:1
	v_pk_mul_f32 v[200:201], v[200:201], v[206:207] op_sel_hi:[1,0]
	s_waitcnt lgkmcnt(6)
	v_add_f32_dpp v146, v146, v146 row_mirror row_mask:0xf bank_mask:0xf bound_ctrl:1
	v_pk_fma_f32 v[198:199], v[146:147], v[190:191], v[198:199] op_sel_hi:[0,1,1] neg_lo:[1,0,0] neg_hi:[1,0,0]
	v_pk_fma_f32 v[200:201], v[146:147], v[192:193], v[200:201] op_sel_hi:[0,1,1] neg_lo:[1,0,0] neg_hi:[1,0,0]
	v_pk_fma_f32 v[138:139], v[138:139], v[194:195], v[198:199]
	v_pk_fma_f32 v[140:141], v[140:141], v[196:197], v[200:201]
	v_pk_mul_f32 v[144:145], v[138:139], v[208:209]
	v_pk_fma_f32 v[144:145], v[140:141], v[210:211], v[144:145]
	v_add_f32 v146, v144, v145
	ds_read_b128 v[164:167], v10 offset:24576
	ds_read_b128 v[168:171], v10 offset:24832
	ds_read_b128 v[172:175], v10 offset:25088
	ds_read_b128 v[176:179], v10 offset:25344
	ds_read_b128 v[180:183], v10 offset:25600
	ds_read_b32 v184, v11 offset:24576
	v_add_f32_dpp v146, v146, v146 quad_perm:[1,0,3,2] row_mask:0xf bank_mask:0xf bound_ctrl:1
	v_pk_mul_f32 v[202:203], v[138:139], v[202:203]
	v_pk_fma_f32 v[202:203], v[140:141], v[204:205], v[202:203]
	v_add_f32_dpp v146, v146, v146 quad_perm:[2,3,0,1] row_mask:0xf bank_mask:0xf bound_ctrl:1
	v_add_f32 v161, v202, v203
	v_pk_mul_f32 v[220:221], v[220:221], v[228:229] op_sel_hi:[1,0]
	v_add_f32_dpp v146, v146, v146 row_half_mirror row_mask:0xf bank_mask:0xf bound_ctrl:1
	v_pk_mul_f32 v[222:223], v[222:223], v[228:229] op_sel_hi:[1,0]
	s_waitcnt lgkmcnt(6)
	v_add_f32_dpp v146, v146, v146 row_mirror row_mask:0xf bank_mask:0xf bound_ctrl:1
	v_pk_fma_f32 v[220:221], v[146:147], v[212:213], v[220:221] op_sel_hi:[0,1,1] neg_lo:[1,0,0] neg_hi:[1,0,0]
	v_pk_fma_f32 v[222:223], v[146:147], v[214:215], v[222:223] op_sel_hi:[0,1,1] neg_lo:[1,0,0] neg_hi:[1,0,0]
	v_pk_fma_f32 v[138:139], v[138:139], v[216:217], v[220:221]
	v_pk_fma_f32 v[140:141], v[140:141], v[218:219], v[222:223]
	v_pk_mul_f32 v[144:145], v[138:139], v[230:231]
	v_pk_fma_f32 v[144:145], v[140:141], v[232:233], v[144:145]
	v_add_f32 v146, v144, v145
	ds_read_b128 v[186:189], v10 offset:26112
	ds_read_b128 v[190:193], v10 offset:26368
	ds_read_b128 v[194:197], v10 offset:26624
	ds_read_b128 v[198:201], v10 offset:26880
	ds_read_b128 v[202:205], v10 offset:27136
	ds_read_b32 v206, v11 offset:26112
	v_add_f32_dpp v146, v146, v146 quad_perm:[1,0,3,2] row_mask:0xf bank_mask:0xf bound_ctrl:1
	v_pk_mul_f32 v[224:225], v[138:139], v[224:225]
	v_pk_fma_f32 v[224:225], v[140:141], v[226:227], v[224:225]
	v_add_f32_dpp v146, v146, v146 quad_perm:[2,3,0,1] row_mask:0xf bank_mask:0xf bound_ctrl:1
	v_add_f32 v162, v224, v225
	v_pk_mul_f32 v[242:243], v[242:243], v[250:251] op_sel_hi:[1,0]
	v_add_f32_dpp v146, v146, v146 row_half_mirror row_mask:0xf bank_mask:0xf bound_ctrl:1
	v_pk_mul_f32 v[244:245], v[244:245], v[250:251] op_sel_hi:[1,0]
	s_waitcnt lgkmcnt(6)
	v_add_f32_dpp v146, v146, v146 row_mirror row_mask:0xf bank_mask:0xf bound_ctrl:1
	v_pk_fma_f32 v[242:243], v[146:147], v[234:235], v[242:243] op_sel_hi:[0,1,1] neg_lo:[1,0,0] neg_hi:[1,0,0]
	v_pk_fma_f32 v[244:245], v[146:147], v[236:237], v[244:245] op_sel_hi:[0,1,1] neg_lo:[1,0,0] neg_hi:[1,0,0]
	v_pk_fma_f32 v[138:139], v[138:139], v[238:239], v[242:243]
	v_pk_fma_f32 v[140:141], v[140:141], v[240:241], v[244:245]
	v_pk_mul_f32 v[144:145], v[138:139], v[164:165]
	v_pk_fma_f32 v[144:145], v[140:141], v[166:167], v[144:145]
	v_add_f32 v146, v144, v145
	ds_read_b128 v[208:211], v10 offset:27648
	ds_read_b128 v[212:215], v10 offset:27904
	ds_read_b128 v[216:219], v10 offset:28160
	ds_read_b128 v[220:223], v10 offset:28416
	ds_read_b128 v[224:227], v10 offset:28672
	ds_read_b32 v228, v11 offset:27648
	v_add_f32_dpp v146, v146, v146 quad_perm:[1,0,3,2] row_mask:0xf bank_mask:0xf bound_ctrl:1
	v_pk_mul_f32 v[246:247], v[138:139], v[246:247]
	v_pk_fma_f32 v[246:247], v[140:141], v[248:249], v[246:247]
	v_add_f32_dpp v146, v146, v146 quad_perm:[2,3,0,1] row_mask:0xf bank_mask:0xf bound_ctrl:1
	v_add_f32 v163, v246, v247
	v_pk_mul_f32 v[176:177], v[176:177], v[184:185] op_sel_hi:[1,0]
	v_add_f32_dpp v146, v146, v146 row_half_mirror row_mask:0xf bank_mask:0xf bound_ctrl:1
	v_pk_mul_f32 v[178:179], v[178:179], v[184:185] op_sel_hi:[1,0]
	s_waitcnt lgkmcnt(6)
	v_add_f32_dpp v146, v146, v146 row_mirror row_mask:0xf bank_mask:0xf bound_ctrl:1
	v_pk_fma_f32 v[176:177], v[146:147], v[168:169], v[176:177] op_sel_hi:[0,1,1] neg_lo:[1,0,0] neg_hi:[1,0,0]
	v_pk_fma_f32 v[178:179], v[146:147], v[170:171], v[178:179] op_sel_hi:[0,1,1] neg_lo:[1,0,0] neg_hi:[1,0,0]
	v_pk_fma_f32 v[138:139], v[138:139], v[172:173], v[176:177]
	v_pk_fma_f32 v[140:141], v[140:141], v[174:175], v[178:179]
	v_pk_mul_f32 v[144:145], v[138:139], v[186:187]
	v_pk_fma_f32 v[144:145], v[140:141], v[188:189], v[144:145]
	v_add_f32 v146, v144, v145
	v_add_f32_dpp v230, v148, v148 row_mirror row_mask:0xf bank_mask:0x3 bound_ctrl:1
	v_add_f32_dpp v230, v156, v156 row_mirror row_mask:0xf bank_mask:0xc bound_ctrl:1
	v_add_f32_dpp v231, v149, v149 row_mirror row_mask:0xf bank_mask:0x3 bound_ctrl:1
	v_add_f32_dpp v231, v157, v157 row_mirror row_mask:0xf bank_mask:0xc bound_ctrl:1
	v_add_f32_dpp v232, v150, v150 row_mirror row_mask:0xf bank_mask:0x3 bound_ctrl:1
	v_add_f32_dpp v232, v158, v158 row_mirror row_mask:0xf bank_mask:0xc bound_ctrl:1
	v_add_f32_dpp v233, v151, v151 row_mirror row_mask:0xf bank_mask:0x3 bound_ctrl:1
	v_add_f32_dpp v233, v159, v159 row_mirror row_mask:0xf bank_mask:0xc bound_ctrl:1
	v_add_f32_dpp v234, v152, v152 row_mirror row_mask:0xf bank_mask:0x3 bound_ctrl:1
	v_add_f32_dpp v234, v160, v160 row_mirror row_mask:0xf bank_mask:0xc bound_ctrl:1
	v_add_f32_dpp v235, v153, v153 row_mirror row_mask:0xf bank_mask:0x3 bound_ctrl:1
	v_add_f32_dpp v235, v161, v161 row_mirror row_mask:0xf bank_mask:0xc bound_ctrl:1
	v_add_f32_dpp v236, v154, v154 row_mirror row_mask:0xf bank_mask:0x3 bound_ctrl:1
	v_add_f32_dpp v236, v162, v162 row_mirror row_mask:0xf bank_mask:0xc bound_ctrl:1
	v_add_f32_dpp v237, v155, v155 row_mirror row_mask:0xf bank_mask:0x3 bound_ctrl:1
	v_add_f32_dpp v237, v163, v163 row_mirror row_mask:0xf bank_mask:0xc bound_ctrl:1
	v_add_f32_dpp v238, v230, v230 row_half_mirror row_mask:0xf bank_mask:0x5 bound_ctrl:1
	v_add_f32_dpp v238, v234, v234 row_half_mirror row_mask:0xf bank_mask:0xa bound_ctrl:1
	v_add_f32_dpp v239, v231, v231 row_half_mirror row_mask:0xf bank_mask:0x5 bound_ctrl:1
	v_add_f32_dpp v239, v235, v235 row_half_mirror row_mask:0xf bank_mask:0xa bound_ctrl:1
	v_add_f32_dpp v240, v232, v232 row_half_mirror row_mask:0xf bank_mask:0x5 bound_ctrl:1
	v_add_f32_dpp v240, v236, v236 row_half_mirror row_mask:0xf bank_mask:0xa bound_ctrl:1
	v_add_f32_dpp v241, v233, v233 row_half_mirror row_mask:0xf bank_mask:0x5 bound_ctrl:1
	v_add_f32_dpp v241, v237, v237 row_half_mirror row_mask:0xf bank_mask:0xa bound_ctrl:1
	s_mov_b32 vcc_lo, 0xcccccccc
	s_mov_b32 vcc_hi, 0xcccccccc
	v_cndmask_b32 v244, v240, v238, vcc
	v_cndmask_b32 v245, v241, v239, vcc
	v_cndmask_b32 v242, v238, v240, vcc
	v_cndmask_b32 v243, v239, v241, vcc
	v_add_f32_dpp v242, v244, v242 quad_perm:[2,3,0,1] row_mask:0xf bank_mask:0xf bound_ctrl:1
	v_add_f32_dpp v243, v245, v243 quad_perm:[2,3,0,1] row_mask:0xf bank_mask:0xf bound_ctrl:1
	s_mov_b32 vcc_lo, 0xaaaaaaaa
	s_mov_b32 vcc_hi, 0xaaaaaaaa
	v_cndmask_b32 v244, v243, v242, vcc
	v_cndmask_b32 v245, v242, v243, vcc
	s_nop 0
	v_add_f32_dpp v18, v244, v245 quad_perm:[1,0,3,2] row_mask:0xf bank_mask:0xf bound_ctrl:1
	ds_read_b128 v[230:233], v10 offset:29184
	ds_read_b128 v[234:237], v10 offset:29440
	ds_read_b128 v[238:241], v10 offset:29696
	ds_read_b128 v[242:245], v10 offset:29952
	ds_read_b128 v[246:249], v10 offset:30208
	ds_read_b32 v250, v11 offset:29184
	v_add_f32_dpp v146, v146, v146 quad_perm:[1,0,3,2] row_mask:0xf bank_mask:0xf bound_ctrl:1
	v_pk_mul_f32 v[180:181], v[138:139], v[180:181]
	v_pk_fma_f32 v[180:181], v[140:141], v[182:183], v[180:181]
	v_add_f32_dpp v146, v146, v146 quad_perm:[2,3,0,1] row_mask:0xf bank_mask:0xf bound_ctrl:1
	v_add_f32 v148, v180, v181
	v_pk_mul_f32 v[198:199], v[198:199], v[206:207] op_sel_hi:[1,0]
	v_add_f32_dpp v146, v146, v146 row_half_mirror row_mask:0xf bank_mask:0xf bound_ctrl:1
	v_pk_mul_f32 v[200:201], v[200:201], v[206:207] op_sel_hi:[1,0]
	s_waitcnt lgkmcnt(6)
	v_add_f32_dpp v146, v146, v146 row_mirror row_mask:0xf bank_mask:0xf bound_ctrl:1
	v_pk_fma_f32 v[198:199], v[146:147], v[190:191], v[198:199] op_sel_hi:[0,1,1] neg_lo:[1,0,0] neg_hi:[1,0,0]
	v_pk_fma_f32 v[200:201], v[146:147], v[192:193], v[200:201] op_sel_hi:[0,1,1] neg_lo:[1,0,0] neg_hi:[1,0,0]
	v_pk_fma_f32 v[138:139], v[138:139], v[194:195], v[198:199]
	v_pk_fma_f32 v[140:141], v[140:141], v[196:197], v[200:201]
	v_pk_mul_f32 v[144:145], v[138:139], v[208:209]
	v_pk_fma_f32 v[144:145], v[140:141], v[210:211], v[144:145]
	v_add_f32 v146, v144, v145
	ds_read_b128 v[164:167], v10 offset:30720
	ds_read_b128 v[168:171], v10 offset:30976
	ds_read_b128 v[172:175], v10 offset:31232
	ds_read_b128 v[176:179], v10 offset:31488
	ds_read_b128 v[180:183], v10 offset:31744
	ds_read_b32 v184, v11 offset:30720
	v_add_f32_dpp v146, v146, v146 quad_perm:[1,0,3,2] row_mask:0xf bank_mask:0xf bound_ctrl:1
	v_pk_mul_f32 v[202:203], v[138:139], v[202:203]
	v_pk_fma_f32 v[202:203], v[140:141], v[204:205], v[202:203]
	v_add_f32_dpp v146, v146, v146 quad_perm:[2,3,0,1] row_mask:0xf bank_mask:0xf bound_ctrl:1
	v_add_f32 v149, v202, v203
	v_pk_mul_f32 v[220:221], v[220:221], v[228:229] op_sel_hi:[1,0]
	v_add_f32_dpp v146, v146, v146 row_half_mirror row_mask:0xf bank_mask:0xf bound_ctrl:1
	v_pk_mul_f32 v[222:223], v[222:223], v[228:229] op_sel_hi:[1,0]
	s_waitcnt lgkmcnt(6)
	v_add_f32_dpp v146, v146, v146 row_mirror row_mask:0xf bank_mask:0xf bound_ctrl:1
	v_pk_fma_f32 v[220:221], v[146:147], v[212:213], v[220:221] op_sel_hi:[0,1,1] neg_lo:[1,0,0] neg_hi:[1,0,0]
	v_pk_fma_f32 v[222:223], v[146:147], v[214:215], v[222:223] op_sel_hi:[0,1,1] neg_lo:[1,0,0] neg_hi:[1,0,0]
	v_pk_fma_f32 v[138:139], v[138:139], v[216:217], v[220:221]
	v_pk_fma_f32 v[140:141], v[140:141], v[218:219], v[222:223]
	v_pk_mul_f32 v[144:145], v[138:139], v[230:231]
	v_pk_fma_f32 v[144:145], v[140:141], v[232:233], v[144:145]
	v_add_f32 v146, v144, v145
	ds_read_b128 v[186:189], v10 offset:32256
	ds_read_b128 v[190:193], v10 offset:32512
	ds_read_b128 v[194:197], v10 offset:32768
	ds_read_b128 v[198:201], v10 offset:33024
	ds_read_b128 v[202:205], v10 offset:33280
	ds_read_b32 v206, v11 offset:32256
	v_add_f32_dpp v146, v146, v146 quad_perm:[1,0,3,2] row_mask:0xf bank_mask:0xf bound_ctrl:1
	v_pk_mul_f32 v[224:225], v[138:139], v[224:225]
	v_pk_fma_f32 v[224:225], v[140:141], v[226:227], v[224:225]
	v_add_f32_dpp v146, v146, v146 quad_perm:[2,3,0,1] row_mask:0xf bank_mask:0xf bound_ctrl:1
	v_add_f32 v150, v224, v225
	v_pk_mul_f32 v[242:243], v[242:243], v[250:251] op_sel_hi:[1,0]
	v_add_f32_dpp v146, v146, v146 row_half_mirror row_mask:0xf bank_mask:0xf bound_ctrl:1
	v_pk_mul_f32 v[244:245], v[244:245], v[250:251] op_sel_hi:[1,0]
	s_waitcnt lgkmcnt(6)
	v_add_f32_dpp v146, v146, v146 row_mirror row_mask:0xf bank_mask:0xf bound_ctrl:1
	v_pk_fma_f32 v[242:243], v[146:147], v[234:235], v[242:243] op_sel_hi:[0,1,1] neg_lo:[1,0,0] neg_hi:[1,0,0]
	v_pk_fma_f32 v[244:245], v[146:147], v[236:237], v[244:245] op_sel_hi:[0,1,1] neg_lo:[1,0,0] neg_hi:[1,0,0]
	v_pk_fma_f32 v[138:139], v[138:139], v[238:239], v[242:243]
	v_pk_fma_f32 v[140:141], v[140:141], v[240:241], v[244:245]
	v_pk_mul_f32 v[144:145], v[138:139], v[164:165]
	v_pk_fma_f32 v[144:145], v[140:141], v[166:167], v[144:145]
	v_add_f32 v146, v144, v145
	ds_read_b128 v[208:211], v10 offset:33792
	ds_read_b128 v[212:215], v10 offset:34048
	ds_read_b128 v[216:219], v10 offset:34304
	ds_read_b128 v[220:223], v10 offset:34560
	ds_read_b128 v[224:227], v10 offset:34816
	ds_read_b32 v228, v11 offset:33792
	v_add_f32_dpp v146, v146, v146 quad_perm:[1,0,3,2] row_mask:0xf bank_mask:0xf bound_ctrl:1
	v_pk_mul_f32 v[246:247], v[138:139], v[246:247]
	v_pk_fma_f32 v[246:247], v[140:141], v[248:249], v[246:247]
	v_add_f32_dpp v146, v146, v146 quad_perm:[2,3,0,1] row_mask:0xf bank_mask:0xf bound_ctrl:1
	v_add_f32 v151, v246, v247
	v_pk_mul_f32 v[176:177], v[176:177], v[184:185] op_sel_hi:[1,0]
	v_add_f32_dpp v146, v146, v146 row_half_mirror row_mask:0xf bank_mask:0xf bound_ctrl:1
	v_pk_mul_f32 v[178:179], v[178:179], v[184:185] op_sel_hi:[1,0]
	s_waitcnt lgkmcnt(6)
	v_add_f32_dpp v146, v146, v146 row_mirror row_mask:0xf bank_mask:0xf bound_ctrl:1
	v_pk_fma_f32 v[176:177], v[146:147], v[168:169], v[176:177] op_sel_hi:[0,1,1] neg_lo:[1,0,0] neg_hi:[1,0,0]
	v_pk_fma_f32 v[178:179], v[146:147], v[170:171], v[178:179] op_sel_hi:[0,1,1] neg_lo:[1,0,0] neg_hi:[1,0,0]
	v_pk_fma_f32 v[138:139], v[138:139], v[172:173], v[176:177]
	v_pk_fma_f32 v[140:141], v[140:141], v[174:175], v[178:179]
	v_pk_mul_f32 v[144:145], v[138:139], v[186:187]
	v_pk_fma_f32 v[144:145], v[140:141], v[188:189], v[144:145]
	v_add_f32 v146, v144, v145
	ds_read_b128 v[230:233], v10 offset:35328
	ds_read_b128 v[234:237], v10 offset:35584
	ds_read_b128 v[238:241], v10 offset:35840
	ds_read_b128 v[242:245], v10 offset:36096
	ds_read_b128 v[246:249], v10 offset:36352
	ds_read_b32 v250, v11 offset:35328
	v_add_f32_dpp v146, v146, v146 quad_perm:[1,0,3,2] row_mask:0xf bank_mask:0xf bound_ctrl:1
	v_pk_mul_f32 v[180:181], v[138:139], v[180:181]
	v_pk_fma_f32 v[180:181], v[140:141], v[182:183], v[180:181]
	v_add_f32_dpp v146, v146, v146 quad_perm:[2,3,0,1] row_mask:0xf bank_mask:0xf bound_ctrl:1
	v_add_f32 v152, v180, v181
	v_pk_mul_f32 v[198:199], v[198:199], v[206:207] op_sel_hi:[1,0]
	v_add_f32_dpp v146, v146, v146 row_half_mirror row_mask:0xf bank_mask:0xf bound_ctrl:1
	v_pk_mul_f32 v[200:201], v[200:201], v[206:207] op_sel_hi:[1,0]
	s_waitcnt lgkmcnt(6)
	v_add_f32_dpp v146, v146, v146 row_mirror row_mask:0xf bank_mask:0xf bound_ctrl:1
	v_pk_fma_f32 v[198:199], v[146:147], v[190:191], v[198:199] op_sel_hi:[0,1,1] neg_lo:[1,0,0] neg_hi:[1,0,0]
	v_pk_fma_f32 v[200:201], v[146:147], v[192:193], v[200:201] op_sel_hi:[0,1,1] neg_lo:[1,0,0] neg_hi:[1,0,0]
	v_pk_fma_f32 v[138:139], v[138:139], v[194:195], v[198:199]
	v_pk_fma_f32 v[140:141], v[140:141], v[196:197], v[200:201]
	v_pk_mul_f32 v[144:145], v[138:139], v[208:209]
	v_pk_fma_f32 v[144:145], v[140:141], v[210:211], v[144:145]
	v_add_f32 v146, v144, v145
	ds_read_b128 v[164:167], v10 offset:36864
	ds_read_b128 v[168:171], v10 offset:37120
	ds_read_b128 v[172:175], v10 offset:37376
	ds_read_b128 v[176:179], v10 offset:37632
	ds_read_b128 v[180:183], v10 offset:37888
	ds_read_b32 v184, v11 offset:36864
	v_add_f32_dpp v146, v146, v146 quad_perm:[1,0,3,2] row_mask:0xf bank_mask:0xf bound_ctrl:1
	v_pk_mul_f32 v[202:203], v[138:139], v[202:203]
	v_pk_fma_f32 v[202:203], v[140:141], v[204:205], v[202:203]
	v_add_f32_dpp v146, v146, v146 quad_perm:[2,3,0,1] row_mask:0xf bank_mask:0xf bound_ctrl:1
	v_add_f32 v153, v202, v203
	v_pk_mul_f32 v[220:221], v[220:221], v[228:229] op_sel_hi:[1,0]
	v_add_f32_dpp v146, v146, v146 row_half_mirror row_mask:0xf bank_mask:0xf bound_ctrl:1
	v_pk_mul_f32 v[222:223], v[222:223], v[228:229] op_sel_hi:[1,0]
	s_waitcnt lgkmcnt(6)
	v_add_f32_dpp v146, v146, v146 row_mirror row_mask:0xf bank_mask:0xf bound_ctrl:1
	v_pk_fma_f32 v[220:221], v[146:147], v[212:213], v[220:221] op_sel_hi:[0,1,1] neg_lo:[1,0,0] neg_hi:[1,0,0]
	v_pk_fma_f32 v[222:223], v[146:147], v[214:215], v[222:223] op_sel_hi:[0,1,1] neg_lo:[1,0,0] neg_hi:[1,0,0]
	v_pk_fma_f32 v[138:139], v[138:139], v[216:217], v[220:221]
	v_pk_fma_f32 v[140:141], v[140:141], v[218:219], v[222:223]
	v_pk_mul_f32 v[144:145], v[138:139], v[230:231]
	v_pk_fma_f32 v[144:145], v[140:141], v[232:233], v[144:145]
	v_add_f32 v146, v144, v145
	ds_read_b128 v[186:189], v10 offset:38400
	ds_read_b128 v[190:193], v10 offset:38656
	ds_read_b128 v[194:197], v10 offset:38912
	ds_read_b128 v[198:201], v10 offset:39168
	ds_read_b128 v[202:205], v10 offset:39424
	ds_read_b32 v206, v11 offset:38400
	v_add_f32_dpp v146, v146, v146 quad_perm:[1,0,3,2] row_mask:0xf bank_mask:0xf bound_ctrl:1
	v_pk_mul_f32 v[224:225], v[138:139], v[224:225]
	v_pk_fma_f32 v[224:225], v[140:141], v[226:227], v[224:225]
	v_add_f32_dpp v146, v146, v146 quad_perm:[2,3,0,1] row_mask:0xf bank_mask:0xf bound_ctrl:1
	v_add_f32 v154, v224, v225
	v_pk_mul_f32 v[242:243], v[242:243], v[250:251] op_sel_hi:[1,0]
	v_add_f32_dpp v146, v146, v146 row_half_mirror row_mask:0xf bank_mask:0xf bound_ctrl:1
	v_pk_mul_f32 v[244:245], v[244:245], v[250:251] op_sel_hi:[1,0]
	s_waitcnt lgkmcnt(6)
	v_add_f32_dpp v146, v146, v146 row_mirror row_mask:0xf bank_mask:0xf bound_ctrl:1
	v_pk_fma_f32 v[242:243], v[146:147], v[234:235], v[242:243] op_sel_hi:[0,1,1] neg_lo:[1,0,0] neg_hi:[1,0,0]
	v_pk_fma_f32 v[244:245], v[146:147], v[236:237], v[244:245] op_sel_hi:[0,1,1] neg_lo:[1,0,0] neg_hi:[1,0,0]
	v_pk_fma_f32 v[138:139], v[138:139], v[238:239], v[242:243]
	v_pk_fma_f32 v[140:141], v[140:141], v[240:241], v[244:245]
	v_pk_mul_f32 v[144:145], v[138:139], v[164:165]
	v_pk_fma_f32 v[144:145], v[140:141], v[166:167], v[144:145]
	v_add_f32 v146, v144, v145
	ds_read_b128 v[208:211], v10 offset:39936
	ds_read_b128 v[212:215], v10 offset:40192
	ds_read_b128 v[216:219], v10 offset:40448
	ds_read_b128 v[220:223], v10 offset:40704
	ds_read_b128 v[224:227], v10 offset:40960
	ds_read_b32 v228, v11 offset:39936
	v_add_f32_dpp v146, v146, v146 quad_perm:[1,0,3,2] row_mask:0xf bank_mask:0xf bound_ctrl:1
	v_pk_mul_f32 v[246:247], v[138:139], v[246:247]
	v_pk_fma_f32 v[246:247], v[140:141], v[248:249], v[246:247]
	v_add_f32_dpp v146, v146, v146 quad_perm:[2,3,0,1] row_mask:0xf bank_mask:0xf bound_ctrl:1
	v_add_f32 v155, v246, v247
	v_pk_mul_f32 v[176:177], v[176:177], v[184:185] op_sel_hi:[1,0]
	v_add_f32_dpp v146, v146, v146 row_half_mirror row_mask:0xf bank_mask:0xf bound_ctrl:1
	v_pk_mul_f32 v[178:179], v[178:179], v[184:185] op_sel_hi:[1,0]
	s_waitcnt lgkmcnt(6)
	v_add_f32_dpp v146, v146, v146 row_mirror row_mask:0xf bank_mask:0xf bound_ctrl:1
	v_pk_fma_f32 v[176:177], v[146:147], v[168:169], v[176:177] op_sel_hi:[0,1,1] neg_lo:[1,0,0] neg_hi:[1,0,0]
	v_pk_fma_f32 v[178:179], v[146:147], v[170:171], v[178:179] op_sel_hi:[0,1,1] neg_lo:[1,0,0] neg_hi:[1,0,0]
	v_pk_fma_f32 v[138:139], v[138:139], v[172:173], v[176:177]
	v_pk_fma_f32 v[140:141], v[140:141], v[174:175], v[178:179]
	v_pk_mul_f32 v[144:145], v[138:139], v[186:187]
	v_pk_fma_f32 v[144:145], v[140:141], v[188:189], v[144:145]
	v_add_f32 v146, v144, v145
	ds_read_b128 v[230:233], v10 offset:41472
	ds_read_b128 v[234:237], v10 offset:41728
	ds_read_b128 v[238:241], v10 offset:41984
	ds_read_b128 v[242:245], v10 offset:42240
	ds_read_b128 v[246:249], v10 offset:42496
	ds_read_b32 v250, v11 offset:41472
	v_add_f32_dpp v146, v146, v146 quad_perm:[1,0,3,2] row_mask:0xf bank_mask:0xf bound_ctrl:1
	v_pk_mul_f32 v[180:181], v[138:139], v[180:181]
	v_pk_fma_f32 v[180:181], v[140:141], v[182:183], v[180:181]
	v_add_f32_dpp v146, v146, v146 quad_perm:[2,3,0,1] row_mask:0xf bank_mask:0xf bound_ctrl:1
	v_add_f32 v156, v180, v181
	v_pk_mul_f32 v[198:199], v[198:199], v[206:207] op_sel_hi:[1,0]
	v_add_f32_dpp v146, v146, v146 row_half_mirror row_mask:0xf bank_mask:0xf bound_ctrl:1
	v_pk_mul_f32 v[200:201], v[200:201], v[206:207] op_sel_hi:[1,0]
	s_waitcnt lgkmcnt(6)
	v_add_f32_dpp v146, v146, v146 row_mirror row_mask:0xf bank_mask:0xf bound_ctrl:1
	v_pk_fma_f32 v[198:199], v[146:147], v[190:191], v[198:199] op_sel_hi:[0,1,1] neg_lo:[1,0,0] neg_hi:[1,0,0]
	v_pk_fma_f32 v[200:201], v[146:147], v[192:193], v[200:201] op_sel_hi:[0,1,1] neg_lo:[1,0,0] neg_hi:[1,0,0]
	v_pk_fma_f32 v[138:139], v[138:139], v[194:195], v[198:199]
	v_pk_fma_f32 v[140:141], v[140:141], v[196:197], v[200:201]
	v_pk_mul_f32 v[144:145], v[138:139], v[208:209]
	v_pk_fma_f32 v[144:145], v[140:141], v[210:211], v[144:145]
	v_add_f32 v146, v144, v145
	ds_read_b128 v[164:167], v10 offset:43008
	ds_read_b128 v[168:171], v10 offset:43264
	ds_read_b128 v[172:175], v10 offset:43520
	ds_read_b128 v[176:179], v10 offset:43776
	ds_read_b128 v[180:183], v10 offset:44032
	ds_read_b32 v184, v11 offset:43008
	v_add_f32_dpp v146, v146, v146 quad_perm:[1,0,3,2] row_mask:0xf bank_mask:0xf bound_ctrl:1
	v_pk_mul_f32 v[202:203], v[138:139], v[202:203]
	v_pk_fma_f32 v[202:203], v[140:141], v[204:205], v[202:203]
	v_add_f32_dpp v146, v146, v146 quad_perm:[2,3,0,1] row_mask:0xf bank_mask:0xf bound_ctrl:1
	v_add_f32 v157, v202, v203
	v_pk_mul_f32 v[220:221], v[220:221], v[228:229] op_sel_hi:[1,0]
	v_add_f32_dpp v146, v146, v146 row_half_mirror row_mask:0xf bank_mask:0xf bound_ctrl:1
	v_pk_mul_f32 v[222:223], v[222:223], v[228:229] op_sel_hi:[1,0]
	s_waitcnt lgkmcnt(6)
	v_add_f32_dpp v146, v146, v146 row_mirror row_mask:0xf bank_mask:0xf bound_ctrl:1
	v_pk_fma_f32 v[220:221], v[146:147], v[212:213], v[220:221] op_sel_hi:[0,1,1] neg_lo:[1,0,0] neg_hi:[1,0,0]
	v_pk_fma_f32 v[222:223], v[146:147], v[214:215], v[222:223] op_sel_hi:[0,1,1] neg_lo:[1,0,0] neg_hi:[1,0,0]
	v_pk_fma_f32 v[138:139], v[138:139], v[216:217], v[220:221]
	v_pk_fma_f32 v[140:141], v[140:141], v[218:219], v[222:223]
	v_pk_mul_f32 v[144:145], v[138:139], v[230:231]
	v_pk_fma_f32 v[144:145], v[140:141], v[232:233], v[144:145]
	v_add_f32 v146, v144, v145
	ds_read_b128 v[186:189], v10 offset:44544
	ds_read_b128 v[190:193], v10 offset:44800
	ds_read_b128 v[194:197], v10 offset:45056
	ds_read_b128 v[198:201], v10 offset:45312
	ds_read_b128 v[202:205], v10 offset:45568
	ds_read_b32 v206, v11 offset:44544
	v_add_f32_dpp v146, v146, v146 quad_perm:[1,0,3,2] row_mask:0xf bank_mask:0xf bound_ctrl:1
	v_pk_mul_f32 v[224:225], v[138:139], v[224:225]
	v_pk_fma_f32 v[224:225], v[140:141], v[226:227], v[224:225]
	v_add_f32_dpp v146, v146, v146 quad_perm:[2,3,0,1] row_mask:0xf bank_mask:0xf bound_ctrl:1
	v_add_f32 v158, v224, v225
	v_pk_mul_f32 v[242:243], v[242:243], v[250:251] op_sel_hi:[1,0]
	v_add_f32_dpp v146, v146, v146 row_half_mirror row_mask:0xf bank_mask:0xf bound_ctrl:1
	v_pk_mul_f32 v[244:245], v[244:245], v[250:251] op_sel_hi:[1,0]
	s_waitcnt lgkmcnt(6)
	v_add_f32_dpp v146, v146, v146 row_mirror row_mask:0xf bank_mask:0xf bound_ctrl:1
	v_pk_fma_f32 v[242:243], v[146:147], v[234:235], v[242:243] op_sel_hi:[0,1,1] neg_lo:[1,0,0] neg_hi:[1,0,0]
	v_pk_fma_f32 v[244:245], v[146:147], v[236:237], v[244:245] op_sel_hi:[0,1,1] neg_lo:[1,0,0] neg_hi:[1,0,0]
	v_pk_fma_f32 v[138:139], v[138:139], v[238:239], v[242:243]
	v_pk_fma_f32 v[140:141], v[140:141], v[240:241], v[244:245]
	v_pk_mul_f32 v[144:145], v[138:139], v[164:165]
	v_pk_fma_f32 v[144:145], v[140:141], v[166:167], v[144:145]
	v_add_f32 v146, v144, v145
	ds_read_b128 v[208:211], v10 offset:46080
	ds_read_b128 v[212:215], v10 offset:46336
	ds_read_b128 v[216:219], v10 offset:46592
	ds_read_b128 v[220:223], v10 offset:46848
	ds_read_b128 v[224:227], v10 offset:47104
	ds_read_b32 v228, v11 offset:46080
	v_add_f32_dpp v146, v146, v146 quad_perm:[1,0,3,2] row_mask:0xf bank_mask:0xf bound_ctrl:1
	v_pk_mul_f32 v[246:247], v[138:139], v[246:247]
	v_pk_fma_f32 v[246:247], v[140:141], v[248:249], v[246:247]
	v_add_f32_dpp v146, v146, v146 quad_perm:[2,3,0,1] row_mask:0xf bank_mask:0xf bound_ctrl:1
	v_add_f32 v159, v246, v247
	v_pk_mul_f32 v[176:177], v[176:177], v[184:185] op_sel_hi:[1,0]
	v_add_f32_dpp v146, v146, v146 row_half_mirror row_mask:0xf bank_mask:0xf bound_ctrl:1
	v_pk_mul_f32 v[178:179], v[178:179], v[184:185] op_sel_hi:[1,0]
	s_waitcnt lgkmcnt(6)
	v_add_f32_dpp v146, v146, v146 row_mirror row_mask:0xf bank_mask:0xf bound_ctrl:1
	v_pk_fma_f32 v[176:177], v[146:147], v[168:169], v[176:177] op_sel_hi:[0,1,1] neg_lo:[1,0,0] neg_hi:[1,0,0]
	v_pk_fma_f32 v[178:179], v[146:147], v[170:171], v[178:179] op_sel_hi:[0,1,1] neg_lo:[1,0,0] neg_hi:[1,0,0]
	v_pk_fma_f32 v[138:139], v[138:139], v[172:173], v[176:177]
	v_pk_fma_f32 v[140:141], v[140:141], v[174:175], v[178:179]
	v_pk_mul_f32 v[144:145], v[138:139], v[186:187]
	v_pk_fma_f32 v[144:145], v[140:141], v[188:189], v[144:145]
	v_add_f32 v146, v144, v145
	ds_read_b128 v[230:233], v10 offset:47616
	ds_read_b128 v[234:237], v10 offset:47872
	ds_read_b128 v[238:241], v10 offset:48128
	ds_read_b128 v[242:245], v10 offset:48384
	ds_read_b128 v[246:249], v10 offset:48640
	ds_read_b32 v250, v11 offset:47616
	v_add_f32_dpp v146, v146, v146 quad_perm:[1,0,3,2] row_mask:0xf bank_mask:0xf bound_ctrl:1
	v_pk_mul_f32 v[180:181], v[138:139], v[180:181]
	v_pk_fma_f32 v[180:181], v[140:141], v[182:183], v[180:181]
	v_add_f32_dpp v146, v146, v146 quad_perm:[2,3,0,1] row_mask:0xf bank_mask:0xf bound_ctrl:1
	v_add_f32 v160, v180, v181
	v_pk_mul_f32 v[198:199], v[198:199], v[206:207] op_sel_hi:[1,0]
	v_add_f32_dpp v146, v146, v146 row_half_mirror row_mask:0xf bank_mask:0xf bound_ctrl:1
	v_pk_mul_f32 v[200:201], v[200:201], v[206:207] op_sel_hi:[1,0]
	s_waitcnt lgkmcnt(6)
	v_add_f32_dpp v146, v146, v146 row_mirror row_mask:0xf bank_mask:0xf bound_ctrl:1
	v_pk_fma_f32 v[198:199], v[146:147], v[190:191], v[198:199] op_sel_hi:[0,1,1] neg_lo:[1,0,0] neg_hi:[1,0,0]
	v_pk_fma_f32 v[200:201], v[146:147], v[192:193], v[200:201] op_sel_hi:[0,1,1] neg_lo:[1,0,0] neg_hi:[1,0,0]
	v_pk_fma_f32 v[138:139], v[138:139], v[194:195], v[198:199]
	v_pk_fma_f32 v[140:141], v[140:141], v[196:197], v[200:201]
	v_pk_mul_f32 v[144:145], v[138:139], v[208:209]
	v_pk_fma_f32 v[144:145], v[140:141], v[210:211], v[144:145]
	v_add_f32 v146, v144, v145
	s_nop 1
	v_add_f32_dpp v146, v146, v146 quad_perm:[1,0,3,2] row_mask:0xf bank_mask:0xf bound_ctrl:1
	v_pk_mul_f32 v[202:203], v[138:139], v[202:203]
	v_pk_fma_f32 v[202:203], v[140:141], v[204:205], v[202:203]
	v_add_f32_dpp v146, v146, v146 quad_perm:[2,3,0,1] row_mask:0xf bank_mask:0xf bound_ctrl:1
	v_add_f32 v161, v202, v203
	v_pk_mul_f32 v[220:221], v[220:221], v[228:229] op_sel_hi:[1,0]
	v_add_f32_dpp v146, v146, v146 row_half_mirror row_mask:0xf bank_mask:0xf bound_ctrl:1
	v_pk_mul_f32 v[222:223], v[222:223], v[228:229] op_sel_hi:[1,0]
	s_waitcnt lgkmcnt(0)
	v_add_f32_dpp v146, v146, v146 row_mirror row_mask:0xf bank_mask:0xf bound_ctrl:1
	v_pk_fma_f32 v[220:221], v[146:147], v[212:213], v[220:221] op_sel_hi:[0,1,1] neg_lo:[1,0,0] neg_hi:[1,0,0]
	v_pk_fma_f32 v[222:223], v[146:147], v[214:215], v[222:223] op_sel_hi:[0,1,1] neg_lo:[1,0,0] neg_hi:[1,0,0]
	v_pk_fma_f32 v[138:139], v[138:139], v[216:217], v[220:221]
	v_pk_fma_f32 v[140:141], v[140:141], v[218:219], v[222:223]
	v_pk_mul_f32 v[144:145], v[138:139], v[230:231]
	v_pk_fma_f32 v[144:145], v[140:141], v[232:233], v[144:145]
	v_add_f32 v146, v144, v145
	s_nop 1
	v_add_f32_dpp v146, v146, v146 quad_perm:[1,0,3,2] row_mask:0xf bank_mask:0xf bound_ctrl:1
	v_pk_mul_f32 v[224:225], v[138:139], v[224:225]
	v_pk_fma_f32 v[224:225], v[140:141], v[226:227], v[224:225]
	v_add_f32_dpp v146, v146, v146 quad_perm:[2,3,0,1] row_mask:0xf bank_mask:0xf bound_ctrl:1
	v_add_f32 v162, v224, v225
	v_pk_mul_f32 v[242:243], v[242:243], v[250:251] op_sel_hi:[1,0]
	v_add_f32_dpp v146, v146, v146 row_half_mirror row_mask:0xf bank_mask:0xf bound_ctrl:1
	v_pk_mul_f32 v[244:245], v[244:245], v[250:251] op_sel_hi:[1,0]
	s_nop 0
	v_add_f32_dpp v146, v146, v146 row_mirror row_mask:0xf bank_mask:0xf bound_ctrl:1
	v_pk_fma_f32 v[242:243], v[146:147], v[234:235], v[242:243] op_sel_hi:[0,1,1] neg_lo:[1,0,0] neg_hi:[1,0,0]
	v_pk_fma_f32 v[244:245], v[146:147], v[236:237], v[244:245] op_sel_hi:[0,1,1] neg_lo:[1,0,0] neg_hi:[1,0,0]
	v_pk_fma_f32 v[138:139], v[138:139], v[238:239], v[242:243]
	v_pk_fma_f32 v[140:141], v[140:141], v[240:241], v[244:245]
	v_pk_mul_f32 v[246:247], v[138:139], v[246:247]
	v_pk_fma_f32 v[246:247], v[140:141], v[248:249], v[246:247]
	v_add_f32 v163, v246, v247
	s_nop 0
	v_add_f32_dpp v230, v148, v148 row_mirror row_mask:0xf bank_mask:0x3 bound_ctrl:1
	v_add_f32_dpp v230, v156, v156 row_mirror row_mask:0xf bank_mask:0xc bound_ctrl:1
	v_add_f32_dpp v231, v149, v149 row_mirror row_mask:0xf bank_mask:0x3 bound_ctrl:1
	v_add_f32_dpp v231, v157, v157 row_mirror row_mask:0xf bank_mask:0xc bound_ctrl:1
	v_add_f32_dpp v232, v150, v150 row_mirror row_mask:0xf bank_mask:0x3 bound_ctrl:1
	v_add_f32_dpp v232, v158, v158 row_mirror row_mask:0xf bank_mask:0xc bound_ctrl:1
	v_add_f32_dpp v233, v151, v151 row_mirror row_mask:0xf bank_mask:0x3 bound_ctrl:1
	v_add_f32_dpp v233, v159, v159 row_mirror row_mask:0xf bank_mask:0xc bound_ctrl:1
	v_add_f32_dpp v234, v152, v152 row_mirror row_mask:0xf bank_mask:0x3 bound_ctrl:1
	v_add_f32_dpp v234, v160, v160 row_mirror row_mask:0xf bank_mask:0xc bound_ctrl:1
	v_add_f32_dpp v235, v153, v153 row_mirror row_mask:0xf bank_mask:0x3 bound_ctrl:1
	v_add_f32_dpp v235, v161, v161 row_mirror row_mask:0xf bank_mask:0xc bound_ctrl:1
	v_add_f32_dpp v236, v154, v154 row_mirror row_mask:0xf bank_mask:0x3 bound_ctrl:1
	v_add_f32_dpp v236, v162, v162 row_mirror row_mask:0xf bank_mask:0xc bound_ctrl:1
	v_add_f32_dpp v237, v155, v155 row_mirror row_mask:0xf bank_mask:0x3 bound_ctrl:1
	v_add_f32_dpp v237, v163, v163 row_mirror row_mask:0xf bank_mask:0xc bound_ctrl:1
	v_add_f32_dpp v238, v230, v230 row_half_mirror row_mask:0xf bank_mask:0x5 bound_ctrl:1
	v_add_f32_dpp v238, v234, v234 row_half_mirror row_mask:0xf bank_mask:0xa bound_ctrl:1
	v_add_f32_dpp v239, v231, v231 row_half_mirror row_mask:0xf bank_mask:0x5 bound_ctrl:1
	v_add_f32_dpp v239, v235, v235 row_half_mirror row_mask:0xf bank_mask:0xa bound_ctrl:1
	v_add_f32_dpp v240, v232, v232 row_half_mirror row_mask:0xf bank_mask:0x5 bound_ctrl:1
	v_add_f32_dpp v240, v236, v236 row_half_mirror row_mask:0xf bank_mask:0xa bound_ctrl:1
	v_add_f32_dpp v241, v233, v233 row_half_mirror row_mask:0xf bank_mask:0x5 bound_ctrl:1
	v_add_f32_dpp v241, v237, v237 row_half_mirror row_mask:0xf bank_mask:0xa bound_ctrl:1
	s_mov_b32 vcc_lo, 0xcccccccc
	s_mov_b32 vcc_hi, 0xcccccccc
	v_cndmask_b32 v244, v240, v238, vcc
	v_cndmask_b32 v245, v241, v239, vcc
	v_cndmask_b32 v242, v238, v240, vcc
	v_cndmask_b32 v243, v239, v241, vcc
	v_add_f32_dpp v242, v244, v242 quad_perm:[2,3,0,1] row_mask:0xf bank_mask:0xf bound_ctrl:1
	v_add_f32_dpp v243, v245, v243 quad_perm:[2,3,0,1] row_mask:0xf bank_mask:0xf bound_ctrl:1
	s_mov_b32 vcc_lo, 0xaaaaaaaa
	s_mov_b32 vcc_hi, 0xaaaaaaaa
	v_cndmask_b32 v244, v243, v242, vcc
	v_cndmask_b32 v245, v242, v243, vcc
	s_nop 0
	v_add_f32_dpp v19, v244, v245 quad_perm:[1,0,3,2] row_mask:0xf bank_mask:0xf bound_ctrl:1

; #define SCAN_BAR() asm volatile("s_barrier" ::: "memory")
; __device__ __forceinline__ void scan_unit(const Ctx& C0, const float* scn, int T, int quarter, const float* S0, float* Sout, unsigned char* obase, int mode) {
;     ...
;             if (mode == 0) { *(float*)(obase + (size_t)(k * 32 + q) * UPITCH_B + rl * 4) = osel0; *(float*)(obase + (size_t)(k * 32 + 16 + q) * UPITCH_B + rl * 4) = osel1; }
;             SCAN_BAR();
;         }
;         if (mode == 0) *(f32x4*)(Sout + irow * 64 + 4 * q) = (f32x4){S0x, S1x, S2x, S3x};
	s_addc_u32 s1, s1, 0
	v_add_co_u32_e32 v16, vcc, s8, v14
	s_cmp_lg_u32 s0, 0x5600000
	s_nop 0
	v_addc_co_u32_e32 v17, vcc, 0, v15, vcc
	v_add_co_u32_e32 v14, vcc, 0xfcaa000, v14
	global_store_dword v[16:17], v18, off offset:768
	s_nop 0
	v_addc_co_u32_e32 v15, vcc, 0, v15, vcc
	global_store_dword v[14:15], v19, off offset:768
	s_barrier
	s_cbranch_scc1 .LBB0_685
	v_mov_b32_e32 v2, v138
	v_mov_b32_e32 v13, v139
	v_mov_b32_e32 v12, v140
	v_mov_b32_e32 v8, v141
	v_readlane_b32 s0, v255, 46
	s_add_i32 s0, s3, s0
	s_ashr_i32 s1, s0, 31
	s_lshl_b64 s[0:1], s[0:1], 17
	v_readlane_b32 s3, v253, 26
	s_add_u32 s0, s3, s0
	v_readlane_b32 s3, v253, 27
	s_addc_u32 s1, s3, s1
	s_lshl_b32 s2, s2, 14
	s_add_u32 s0, s0, s2
	s_addc_u32 s1, s1, 0
	v_lshlrev_b32_e32 v0, 8, v0
	v_lshl_add_u64 v[6:7], s[0:1], 0, v[0:1]
	v_mov_b32_e32 v5, v1
	v_lshl_add_u64 v[6:7], v[6:7], 0, v[4:5]
	v_mov_b32_e32 v3, v13
	v_mov_b32_e32 v4, v12
	v_mov_b32_e32 v5, v8
	global_store_dwordx4 v[6:7], v[2:5], off
